# mixer: nt (non-temporal) hint removed from the 40 proj loads of the pooling/gating mixer (data was just written by the in-projection and is cache resident)
# baseline (speedup 1.0000x reference)
; #define LAS __attribute__((address_space(3)))
; #define tid  (fresh_tid_w(wave_s))
; #define lane (hw_lane())
; __device__ __forceinline__ void pool_load(const bf16* proj, int it, int lane, v4u (&raw)[12]) {
;     const int chunk = it >> 4, g = (it >> 2) & 3, rq = it & 3; proj += (size_t)(chunk >> 6) * GAP_P;
;     const size_t R0 = (size_t)chunk * 128 + rq * 32; const int tseq = (int)(R0 & (SEQ - 1)), r = lane & 15, q = lane >> 4;
; #pragma unroll
;     for (int i = 0; i < 12; ++i) { const int row = q + 4 * i; raw[i] = (v4u){0u, 0u, 0u, 0u};
;         if (row >= 16 || tseq != 0) raw[i] = __builtin_nontemporal_load((const v4u*)(proj + (R0 + row - 16) * DIN + g * 128 + r * 8)); }
; __device__ __forceinline__ void mixer_phase(LAS unsigned char* lds, const bf16* proj, bf16* ymix, const float* vstat, const bf16* WpT, const float* pscale, const float* sgu_g, const bf16* Wm, const float* sgu_b, int pool_first, int pool_step, int pool_limit, int sgu_first, int sgu_step, int sgu_limi ...
;     int tid = tid_in; asm volatile("" : "+v"(tid));
;     const int lane = tid & 63, wave = __builtin_amdgcn_readfirstlane(tid >> 6);
;     LAS unsigned char* wl = lds + wave * MIXW;
;     { v4u raw[12]; if (pool_first < pool_limit) pool_load(proj, pool_first, lane, raw);
.LBB0_492:
	s_mov_b64 s[26:27], s[58:59]
	s_mov_b64 s[20:21], s[58:59]
	s_mov_b64 s[38:39], s[58:59]
	v_mbcnt_lo_u32_b32 v0, -1, 0
	v_mbcnt_hi_u32_b32 v0, -1, v0
	s_nop 0
	v_or_b32_e32 v81, s93, v0
	s_nop 0
	s_nop 0
	v_readfirstlane_b32 s0, v81
	s_lshr_b32 s10, s0, 6
	v_readlane_b32 s0, v254, 42
	v_and_b32_e32 v140, 63, v81
	s_mulk_i32 s10, 0x3300
	v_readlane_b32 s1, v254, 43
	s_add_i32 s2, s10, 0x100
	s_andn2_b64 vcc, exec, s[0:1]
	v_lshlrev_b32_e32 v83, 3, v140
	s_cbranch_vccnz .LBB0_508
	s_add_u32 s9, s26, 0xf100000
	s_addc_u32 s12, s27, 0
	v_readlane_b32 s0, v255, 19
	v_readlane_b32 s6, v254, 46
	s_add_u32 s0, s9, s0
	v_readlane_b32 s1, v255, 18
	v_and_b32_e32 v0, 0x78, v83
	v_readlane_b32 s7, v254, 47
	s_addc_u32 s1, s12, s1
	v_lshrrev_b32_e32 v80, 4, v140
	s_andn2_b64 vcc, exec, s[6:7]
	s_mul_i32 s11, s5, 0xc00
	v_lshlrev_b32_e32 v192, 1, v0
	s_cbranch_vccnz .LBB0_495
	v_or_b32_e32 v4, s4, v80
	v_mov_b64_e32 v[0:1], s[0:1]
	s_movk_i32 s7, 0xc00
	v_mad_u64_u32 v[2:3], s[4:5], v4, s7, v[0:1]
	v_readlane_b32 s4, v254, 48
	v_add_u32_e32 v3, s11, v3
	s_lshl_b32 s86, s4, 1
	v_or_b32_e32 v4, 4, v4
	v_lshl_add_u64 v[2:3], v[2:3], 0, s[86:87]
	v_mad_u64_u32 v[0:1], s[4:5], v4, s7, v[0:1]
	v_lshl_add_u64 v[2:3], v[2:3], 0, v[192:193]
	v_add_u32_e32 v1, s11, v1
	v_add_co_u32_e32 v2, vcc, s83, v2
	v_lshl_add_u64 v[0:1], v[0:1], 0, s[86:87]
	s_nop 0
	v_addc_co_u32_e32 v3, vcc, -1, v3, vcc
	v_lshl_add_u64 v[0:1], v[0:1], 0, v[192:193]
	v_add_co_u32_e32 v4, vcc, 0xffff4000, v0
	s_nop 1
	v_addc_co_u32_e32 v5, vcc, -1, v1, vcc
	global_load_dwordx4 v[0:3], v[2:3], off
	s_nop 0
	global_load_dwordx4 v[4:7], v[4:5], off
	s_branch .LBB0_496

; #define lane (hw_lane())
; __device__ __forceinline__ void pool_load(const bf16* proj, int it, int lane, v4u (&raw)[12]) {
;     const int chunk = it >> 4, g = (it >> 2) & 3, rq = it & 3; proj += (size_t)(chunk >> 6) * GAP_P;
;     const size_t R0 = (size_t)chunk * 128 + rq * 32; const int tseq = (int)(R0 & (SEQ - 1)), r = lane & 15, q = lane >> 4;
; #pragma unroll
;     for (int i = 0; i < 12; ++i) { const int row = q + 4 * i; raw[i] = (v4u){0u, 0u, 0u, 0u};
;         if (row >= 16 || tseq != 0) raw[i] = __builtin_nontemporal_load((const v4u*)(proj + (R0 + row - 16) * DIN + g * 128 + r * 8)); }
.LBB0_496:
	v_readlane_b32 s4, v254, 46
	v_readlane_b32 s5, v254, 47
	v_or_b32_e32 v82, 8, v80
	s_and_b64 vcc, exec, s[4:5]
	v_or_b32_e32 v16, 12, v80
	s_cbranch_vccz .LBB0_525
	v_readlane_b32 s6, v254, 44
	v_readlane_b32 s7, v254, 45
	s_movk_i32 s7, 0xc00
	v_or_b32_e32 v10, s6, v82
	v_mov_b64_e32 v[8:9], s[0:1]
	v_mad_u64_u32 v[10:11], s[4:5], v10, s7, v[8:9]
	v_readlane_b32 s4, v254, 48
	v_or_b32_e32 v48, 12, v80
	v_add_u32_e32 v11, s11, v11
	s_lshl_b32 s86, s4, 1
	v_or_b32_e32 v12, s6, v48
	v_lshl_add_u64 v[10:11], v[10:11], 0, s[86:87]
	v_mad_u64_u32 v[8:9], s[4:5], v12, s7, v[8:9]
	v_lshl_add_u64 v[10:11], v[10:11], 0, v[192:193]
	v_add_u32_e32 v9, s11, v9
	v_add_co_u32_e32 v10, vcc, s83, v10
	v_lshl_add_u64 v[8:9], v[8:9], 0, s[86:87]
	s_nop 0
	v_addc_co_u32_e32 v11, vcc, -1, v11, vcc
	v_lshl_add_u64 v[8:9], v[8:9], 0, v[192:193]
	v_add_co_u32_e32 v12, vcc, 0xffff4000, v8
	v_mov_b32_e32 v49, v193
	s_nop 0
	v_addc_co_u32_e32 v13, vcc, -1, v9, vcc
	global_load_dwordx4 v[8:11], v[10:11], off
	s_nop 0
	global_load_dwordx4 v[12:15], v[12:13], off
	v_mov_b64_e32 v[84:85], v[48:49]
	s_cbranch_execnz .LBB0_499

; #define LAS __attribute__((address_space(3)))
; #define LDS_WAIT() asm volatile("s_waitcnt lgkmcnt(0)" ::: "memory")
; #define lane (hw_lane())
; __device__ __forceinline__ void pool_load(const bf16* proj, int it, int lane, v4u (&raw)[12]) {
;     ...
; #pragma unroll
;     for (int i = 0; i < 12; ++i) { const int row = q + 4 * i; raw[i] = (v4u){0u, 0u, 0u, 0u};
;         if (row >= 16 || tseq != 0) raw[i] = __builtin_nontemporal_load((const v4u*)(proj + (R0 + row - 16) * DIN + g * 128 + r * 8)); }
; }
; __device__ __forceinline__ void pool_item(LAS unsigned char* wl, const bf16* proj, bf16* ymix, const bf16* WpT, const float* pscale, int chunk, int g, int rq, int lane, v4u (&raw)[12], int nxt_it) {
;     ymix += (size_t)(chunk >> 6) * GAP_Y;
;     const size_t R0 = (size_t)chunk * 128 + rq * 32; const int tseq = (int)(R0 & (SEQ - 1));
;     const int r = lane & 15, q = lane >> 4, win = 2 << g;
; #pragma unroll
;     for (int i = 0; i < 12; ++i) *(LAS v4u*)(wl + (q + 4 * i) * PP + r * 16) = raw[i];
;     LDS_WAIT();
;     if (nxt_it >= 0) pool_load(proj, nxt_it, lane, raw);
.LBB0_499:
	v_readlane_b32 s4, v254, 44
	v_or_b32_e32 v86, 44, v80
	v_mov_b32_e32 v87, v193
	v_readlane_b32 s5, v254, 45
	v_mov_b64_e32 v[40:41], s[0:1]
	s_add_u32 s13, s20, 0x10900000
	v_lshl_add_u64 v[16:17], s[4:5], 0, v[86:87]
	v_mad_u64_u32 v[18:19], s[0:1], v16, s7, v[40:41]
	v_mov_b32_e32 v16, v19
	v_mad_u64_u32 v[16:17], s[0:1], v17, s7, v[16:17]
	v_readlane_b32 s0, v254, 48
	v_or_b32_e32 v90, 36, v80
	v_mov_b32_e32 v91, v193
	s_addc_u32 s14, s21, 0
	v_mov_b32_e32 v19, v16
	s_lshl_b32 s86, s0, 1
	v_or_b32_e32 v88, 40, v80
	v_mov_b32_e32 v89, v193
	v_lshl_add_u64 v[24:25], s[4:5], 0, v[90:91]
	v_lshl_add_u64 v[16:17], v[18:19], 0, s[86:87]
	v_lshl_add_u64 v[18:19], s[4:5], 0, v[88:89]
	v_mad_u64_u32 v[26:27], s[0:1], v24, s7, v[40:41]
	v_mad_u64_u32 v[20:21], s[0:1], v18, s7, v[40:41]
	v_mov_b32_e32 v24, v27
	v_mov_b32_e32 v18, v21
	v_mad_u64_u32 v[24:25], s[0:1], v25, s7, v[24:25]
	v_mad_u64_u32 v[18:19], s[0:1], v19, s7, v[18:19]
	v_mov_b32_e32 v27, v24
	v_or_b32_e32 v92, 32, v80
	v_mov_b32_e32 v93, v193
	v_lshl_add_u64 v[16:17], v[16:17], 0, v[192:193]
	v_mov_b32_e32 v21, v18
	v_lshl_add_u64 v[24:25], v[26:27], 0, s[86:87]
	v_lshl_add_u64 v[26:27], s[4:5], 0, v[92:93]
	v_add_co_u32_e32 v16, vcc, s83, v16
	v_lshl_add_u64 v[18:19], v[20:21], 0, s[86:87]
	v_mad_u64_u32 v[28:29], s[0:1], v26, s7, v[40:41]
	v_addc_co_u32_e32 v17, vcc, -1, v17, vcc
	v_lshl_add_u64 v[18:19], v[18:19], 0, v[192:193]
	v_mov_b32_e32 v26, v29
	v_add_co_u32_e32 v18, vcc, s83, v18
	v_mad_u64_u32 v[26:27], s[0:1], v27, s7, v[26:27]
	s_nop 0
	v_addc_co_u32_e32 v19, vcc, -1, v19, vcc
	v_lshl_add_u64 v[24:25], v[24:25], 0, v[192:193]
	v_mov_b32_e32 v29, v26
	v_add_co_u32_e32 v24, vcc, s83, v24
	v_lshl_add_u64 v[26:27], v[28:29], 0, s[86:87]
	s_nop 0
	v_addc_co_u32_e32 v25, vcc, -1, v25, vcc
	v_lshl_add_u64 v[26:27], v[26:27], 0, v[192:193]
	v_add_co_u32_e32 v26, vcc, s83, v26
	v_or_b32_e32 v94, 28, v80
	global_load_dwordx4 v[20:23], v[16:17], off
	s_nop 0
	global_load_dwordx4 v[16:19], v[18:19], off
	v_addc_co_u32_e32 v27, vcc, -1, v27, vcc
	global_load_dwordx4 v[36:39], v[24:25], off
	global_load_dwordx4 v[32:35], v[26:27], off
	v_or_b32_e32 v24, s4, v94
	v_mad_u64_u32 v[24:25], s[0:1], v24, s7, v[40:41]
	v_or_b32_e32 v96, 24, v80
	v_add_u32_e32 v25, s11, v25
	v_or_b32_e32 v26, s4, v96
	v_lshl_add_u64 v[24:25], v[24:25], 0, s[86:87]
	v_mad_u64_u32 v[26:27], s[0:1], v26, s7, v[40:41]
	v_or_b32_e32 v98, 20, v80
	v_lshl_add_u64 v[24:25], v[24:25], 0, v[192:193]
	v_add_u32_e32 v27, s11, v27
	v_or_b32_e32 v42, s4, v98
	v_add_co_u32_e32 v24, vcc, s83, v24
	v_lshl_add_u64 v[26:27], v[26:27], 0, s[86:87]
	v_mad_u64_u32 v[42:43], s[0:1], v42, s7, v[40:41]
	v_or_b32_e32 v100, 16, v80
	v_addc_co_u32_e32 v25, vcc, -1, v25, vcc
	v_lshl_add_u64 v[26:27], v[26:27], 0, v[192:193]
	v_add_u32_e32 v43, s11, v43
	v_or_b32_e32 v44, s4, v100
	v_add_co_u32_e32 v26, vcc, s83, v26
	v_lshl_add_u64 v[42:43], v[42:43], 0, s[86:87]
	v_mad_u64_u32 v[40:41], s[0:1], v44, s7, v[40:41]
	v_addc_co_u32_e32 v27, vcc, -1, v27, vcc
	v_lshl_add_u64 v[42:43], v[42:43], 0, v[192:193]
	v_add_u32_e32 v41, s11, v41
	v_add_co_u32_e32 v42, vcc, s83, v42
	v_lshl_add_u64 v[40:41], v[40:41], 0, s[86:87]
	s_nop 0
	v_addc_co_u32_e32 v43, vcc, -1, v43, vcc
	v_lshl_add_u64 v[40:41], v[40:41], 0, v[192:193]
	v_add_co_u32_e32 v40, vcc, s83, v40
	global_load_dwordx4 v[28:31], v[24:25], off
	s_nop 0
	global_load_dwordx4 v[24:27], v[26:27], off
	v_addc_co_u32_e32 v41, vcc, -1, v41, vcc
	global_load_dwordx4 v[44:47], v[42:43], off
	s_nop 0
	global_load_dwordx4 v[40:43], v[40:41], off
	v_and_b32_e32 v49, 15, v81
	v_lshlrev_b32_e32 v104, 3, v80
	v_lshlrev_b32_e32 v50, 4, v49
	v_mul_i32_i24_e32 v52, 0x110, v48
	v_or_b32_e32 v106, 1, v104
	v_lshlrev_b32_e32 v48, 3, v49
	v_mov_b32_e32 v49, s10
	s_movk_i32 s0, 0x880
	v_add_u32_e32 v95, s2, v50
	v_mul_u32_u24_e32 v51, 0x110, v80
	v_mul_u32_u24_e32 v53, 0x880, v80
	v_mul_u32_u24_e32 v54, 0x110, v106
	v_mad_u32_u24 v49, v80, s0, v49
	v_readlane_b32 s0, v255, 23
	v_or_b32_e32 v102, 4, v80
	v_or_b32_e32 v108, 2, v104
	v_or_b32_e32 v110, 3, v104
	v_or_b32_e32 v112, 4, v104
	v_or_b32_e32 v114, 5, v104
	v_or_b32_e32 v116, 6, v104
	v_or_b32_e32 v118, 7, v104
	v_add3_u32 v97, v49, v50, s0
	v_add_u32_e32 v99, v95, v51
	v_add_u32_e32 v101, v95, v52
	v_add_u32_e32 v103, v95, v53
	v_add_u32_e32 v105, v95, v54
	v_lshlrev_b32_e32 v120, 1, v48
	v_readlane_b32 s22, v254, 60
.LBB0_500:
	s_add_i32 s15, s22, s77
	v_readlane_b32 s4, v254, 41
	s_cmp_ge_i32 s15, s4
	s_waitcnt vmcnt(0) lgkmcnt(0)
	ds_write_b128 v99, v[0:3]
	ds_write_b128 v99, v[4:7] offset:1088
	ds_write_b128 v99, v[8:11] offset:2176
	ds_write_b128 v101, v[12:15]
	ds_write_b128 v99, v[40:43] offset:4352
	ds_write_b128 v99, v[44:47] offset:5440
	ds_write_b128 v99, v[24:27] offset:6528
	ds_write_b128 v99, v[28:31] offset:7616
	ds_write_b128 v99, v[32:35] offset:8704
	ds_write_b128 v99, v[36:39] offset:9792
	ds_write_b128 v99, v[16:19] offset:10880
	ds_write_b128 v99, v[20:23] offset:11968
	s_cselect_b64 s[0:1], -1, 0
	s_cmp_lt_i32 s15, s4
	s_waitcnt lgkmcnt(0)
	s_cselect_b32 s23, s15, -1
	s_cmp_lt_i32 s23, 0
	s_cbranch_scc1 .LBB0_505
	s_lshr_b32 s4, s23, 10
	s_lshr_b32 s86, s23, 4
	s_mul_hi_u32 s5, s4, 0x1400000
	s_mul_i32 s4, s4, 0x1400000
	s_add_u32 s10, s9, s4
	s_addc_u32 s11, s12, s5
	s_lshl_b32 s23, s23, 5
	s_lshl_b64 s[4:5], s[86:87], 7
	s_and_b32 s6, s23, 0x60
	s_or_b32 s4, s4, s6
	s_and_b32 s86, s4, 0x1fe0
	s_and_b32 s23, s23, 0x180
	s_cmp_eq_u64 s[86:87], 0
	s_cbranch_scc1 .LBB0_503
	v_or_b32_e32 v0, s4, v80
	v_mov_b64_e32 v[8:9], s[10:11]
	v_mad_u64_u32 v[0:1], s[24:25], v0, s7, v[8:9]
	v_mad_u32_u24 v1, s5, v242, v1
	s_lshl_b32 s86, s23, 1
	v_or_b32_e32 v2, s4, v102
	v_lshl_add_u64 v[0:1], v[0:1], 0, s[86:87]
	v_mad_u64_u32 v[2:3], s[24:25], v2, s7, v[8:9]
	v_lshl_add_u64 v[0:1], v[0:1], 0, v[192:193]
	v_mad_u32_u24 v3, s5, v242, v3
	v_or_b32_e32 v10, s4, v82
	v_or_b32_e32 v12, s4, v84
	v_add_co_u32_e32 v0, vcc, s83, v0
	v_lshl_add_u64 v[2:3], v[2:3], 0, s[86:87]
	v_mad_u64_u32 v[10:11], s[24:25], v10, s7, v[8:9]
	v_mad_u64_u32 v[8:9], s[24:25], v12, s7, v[8:9]
	v_addc_co_u32_e32 v1, vcc, -1, v1, vcc
	v_lshl_add_u64 v[2:3], v[2:3], 0, v[192:193]
	v_mad_u32_u24 v11, s5, v242, v11
	v_or_b32_e32 v13, s5, v85
	v_mov_b32_e32 v12, v9
	v_add_co_u32_e32 v4, vcc, s83, v2
	v_lshl_add_u64 v[10:11], v[10:11], 0, s[86:87]
	v_mad_u64_u32 v[12:13], s[24:25], v13, s7, v[12:13]
	v_addc_co_u32_e32 v5, vcc, -1, v3, vcc
	v_lshl_add_u64 v[10:11], v[10:11], 0, v[192:193]
	v_mov_b32_e32 v9, v12
	v_add_co_u32_e32 v10, vcc, s83, v10
	v_lshl_add_u64 v[8:9], v[8:9], 0, s[86:87]
	s_nop 0
	v_addc_co_u32_e32 v11, vcc, -1, v11, vcc
	v_lshl_add_u64 v[8:9], v[8:9], 0, v[192:193]
	v_add_co_u32_e32 v12, vcc, 0xffff4000, v8
	global_load_dwordx4 v[0:3], v[0:1], off
	s_nop 0
	global_load_dwordx4 v[4:7], v[4:5], off
	v_addc_co_u32_e32 v13, vcc, -1, v9, vcc
	global_load_dwordx4 v[8:11], v[10:11], off
	s_nop 0
	global_load_dwordx4 v[12:15], v[12:13], off
	s_branch .LBB0_504

; __device__ __forceinline__ void pool_load(const bf16* proj, int it, int lane, v4u (&raw)[12]) {
;     ...
; #pragma unroll
;     for (int i = 0; i < 12; ++i) { const int row = q + 4 * i; raw[i] = (v4u){0u, 0u, 0u, 0u};
;         if (row >= 16 || tseq != 0) raw[i] = __builtin_nontemporal_load((const v4u*)(proj + (R0 + row - 16) * DIN + g * 128 + r * 8)); }
.LBB0_504:
	v_or_b32_e32 v18, s4, v100
	v_mov_b64_e32 v[16:17], s[10:11]
	v_mad_u64_u32 v[18:19], s[10:11], v18, s7, v[16:17]
	v_mad_u32_u24 v19, s5, v242, v19
	s_lshl_b32 s86, s23, 1
	v_or_b32_e32 v20, s4, v98
	v_lshl_add_u64 v[18:19], v[18:19], 0, s[86:87]
	v_mad_u64_u32 v[20:21], s[10:11], v20, s7, v[16:17]
	v_lshl_add_u64 v[18:19], v[18:19], 0, v[192:193]
	v_mad_u32_u24 v21, s5, v242, v21
	v_add_co_u32_e32 v18, vcc, s83, v18
	v_lshl_add_u64 v[20:21], v[20:21], 0, s[86:87]
	s_nop 0
	v_addc_co_u32_e32 v19, vcc, -1, v19, vcc
	v_lshl_add_u64 v[20:21], v[20:21], 0, v[192:193]
	v_add_co_u32_e32 v20, vcc, s83, v20
	s_nop 1
	v_addc_co_u32_e32 v21, vcc, -1, v21, vcc
	global_load_dwordx4 v[40:43], v[18:19], off
	global_load_dwordx4 v[44:47], v[20:21], off
	v_or_b32_e32 v18, s4, v96
	v_mad_u64_u32 v[18:19], s[10:11], v18, s7, v[16:17]
	v_mad_u32_u24 v19, s5, v242, v19
	v_or_b32_e32 v20, s4, v94
	v_lshl_add_u64 v[18:19], v[18:19], 0, s[86:87]
	v_mad_u64_u32 v[20:21], s[10:11], v20, s7, v[16:17]
	v_lshl_add_u64 v[18:19], v[18:19], 0, v[192:193]
	v_mad_u32_u24 v21, s5, v242, v21
	v_add_co_u32_e32 v18, vcc, s83, v18
	v_lshl_add_u64 v[20:21], v[20:21], 0, s[86:87]
	s_nop 0
	v_addc_co_u32_e32 v19, vcc, -1, v19, vcc
	v_lshl_add_u64 v[20:21], v[20:21], 0, v[192:193]
	v_add_co_u32_e32 v20, vcc, s83, v20
	s_nop 1
	v_addc_co_u32_e32 v21, vcc, -1, v21, vcc
	global_load_dwordx4 v[24:27], v[18:19], off
	global_load_dwordx4 v[28:31], v[20:21], off
	v_lshl_add_u64 v[18:19], s[4:5], 0, v[92:93]
	v_mad_u64_u32 v[20:21], s[10:11], v18, s7, v[16:17]
	v_mad_u32_u24 v21, v19, s7, v21
	v_lshl_add_u64 v[18:19], v[20:21], 0, s[86:87]
	v_lshl_add_u64 v[20:21], s[4:5], 0, v[90:91]
	v_mad_u64_u32 v[22:23], s[10:11], v20, s7, v[16:17]
	v_lshl_add_u64 v[18:19], v[18:19], 0, v[192:193]
	v_mad_u32_u24 v23, v21, s7, v23
	v_add_co_u32_e32 v18, vcc, s83, v18
	v_lshl_add_u64 v[20:21], v[22:23], 0, s[86:87]
	s_nop 0
	v_addc_co_u32_e32 v19, vcc, -1, v19, vcc
	v_lshl_add_u64 v[20:21], v[20:21], 0, v[192:193]
	v_add_co_u32_e32 v20, vcc, s83, v20
	s_nop 1
	v_addc_co_u32_e32 v21, vcc, -1, v21, vcc
	global_load_dwordx4 v[32:35], v[18:19], off
	global_load_dwordx4 v[36:39], v[20:21], off
	v_lshl_add_u64 v[18:19], s[4:5], 0, v[88:89]
	v_mad_u64_u32 v[20:21], s[10:11], v18, s7, v[16:17]
	v_mad_u32_u24 v21, v19, s7, v21
	v_lshl_add_u64 v[18:19], v[20:21], 0, s[86:87]
	v_lshl_add_u64 v[20:21], s[4:5], 0, v[86:87]
	v_mad_u64_u32 v[16:17], s[4:5], v20, s7, v[16:17]
	v_lshl_add_u64 v[18:19], v[18:19], 0, v[192:193]
	v_mad_u32_u24 v17, v21, s7, v17
	v_add_co_u32_e32 v18, vcc, s83, v18
	v_lshl_add_u64 v[16:17], v[16:17], 0, s[86:87]
	s_nop 0
	v_addc_co_u32_e32 v19, vcc, -1, v19, vcc
	v_lshl_add_u64 v[16:17], v[16:17], 0, v[192:193]
	v_add_co_u32_e32 v20, vcc, 0xffff4000, v16
	s_nop 1
	v_addc_co_u32_e32 v21, vcc, -1, v17, vcc
	global_load_dwordx4 v[16:19], v[18:19], off
	s_nop 0
	global_load_dwordx4 v[20:23], v[20:21], off

; #define LAS __attribute__((address_space(3)))
; __device__ __forceinline__ unsigned pk2(float lo, float hi) { return f2bf(lo) | (f2bf(hi) << 16); }
; __device__ __forceinline__ float bflo(unsigned w) { return __uint_as_float(w << 16); }
; __device__ __forceinline__ float bfhi(unsigned w) { return __uint_as_float(w & 0xffff0000u); }
; __device__ __forceinline__ void sgu_item(LAS unsigned char* wl, const bf16* proj, bf16* ymix, const float* vstat, const float* sgu_g, const bf16* Wm, const float* sgu_b, int chunk, int h, int lane) {
;     ...
;     for (int dq = 0; dq < 4; ++dq) {
;         const int colv = h * 128 + dq * 32;
;         v4u raw[8];
; #pragma unroll
;         for (int i = 0; i < 8; ++i) raw[i] = __builtin_nontemporal_load((const v4u*)(proj + (R0 + rsub + 16 * i) * DIN + 1024 + colv + c16 * 8));
;         const f32x4 g0 = *(const f32x4*)(sgu_g + colv + c16 * 8), g1 = *(const f32x4*)(sgu_g + colv + c16 * 8 + 4);
; #pragma unroll
;         for (int i = 0; i < 8; ++i) { const int s = rsub + 16 * i; const f32x2 ms = st[s]; const v4u w = raw[i];
;             v2u lo, hi; lo.x = pk2((bflo(w.x) - ms.x) * ms.y * g0[0], (bfhi(w.x) - ms.x) * ms.y * g0[1]); lo.y = pk2((bflo(w.y) - ms.x) * ms.y * g0[2], (bfhi(w.y) - ms.x) * ms.y * g0[3]);
;             hi.x = pk2((bflo(w.z) - ms.x) * ms.y * g1[0], (bfhi(w.z) - ms.x) * ms.y * g1[1]); hi.y = pk2((bflo(w.w) - ms.x) * ms.y * g1[2], (bfhi(w.w) - ms.x) * ms.y * g1[3]);
;             *(LAS v2u*)(wl + s * VP2 + (4 * c16) * 2) = lo; *(LAS v2u*)(wl + s * VP2 + (16 + 4 * c16) * 2) = hi; }
.LBB0_511:
	v_lshl_add_u64 v[80:81], v[198:199], 0, s[20:21]
	v_add_co_u32_e32 v82, vcc, 0xf100000, v80
	s_mov_b32 s0, 0xf100000
	s_nop 0
	v_addc_co_u32_e32 v83, vcc, 0, v81, vcc
	global_load_dwordx4 v[118:121], v[82:83], off offset:2048
	v_add_co_u32_e32 v82, vcc, 0xf10c000, v80
	s_waitcnt vmcnt(0) lgkmcnt(0)
	v_lshlrev_b32_e32 v117, 16, v119
	v_addc_co_u32_e32 v83, vcc, 0, v81, vcc
	global_load_dwordx4 v[112:115], v[82:83], off offset:2048
	v_add_co_u32_e32 v82, vcc, 0xf118000, v80
	v_lshlrev_b32_e32 v116, 16, v118
	s_nop 0
	v_addc_co_u32_e32 v83, vcc, 0, v81, vcc
	global_load_dwordx4 v[108:111], v[82:83], off offset:2048
	v_add_co_u32_e32 v82, vcc, 0xf124000, v80
	v_and_b32_e32 v119, 0xffff0000, v119
	s_nop 0
	v_addc_co_u32_e32 v83, vcc, 0, v81, vcc
	global_load_dwordx4 v[104:107], v[82:83], off offset:2048
	v_add_co_u32_e32 v82, vcc, 0xf130000, v80
	v_and_b32_e32 v118, 0xffff0000, v118
	s_nop 0
	v_addc_co_u32_e32 v83, vcc, 0, v81, vcc
	global_load_dwordx4 v[100:103], v[82:83], off offset:2048
	v_add_co_u32_e32 v82, vcc, 0xf13c000, v80
	s_nop 1
	v_addc_co_u32_e32 v83, vcc, 0, v81, vcc
	global_load_dwordx4 v[96:99], v[82:83], off offset:2048
	v_add_co_u32_e32 v82, vcc, 0xf148000, v80
	s_nop 1
	v_addc_co_u32_e32 v83, vcc, 0, v81, vcc
	v_add_co_u32_e32 v80, vcc, 0xf154000, v80
	global_load_dwordx4 v[84:87], v[82:83], off offset:2048
	s_nop 0
	v_addc_co_u32_e32 v81, vcc, 0, v81, vcc
	global_load_dwordx4 v[80:83], v[80:81], off offset:2048
	s_nop 0
	global_load_dwordx4 v[88:91], v[178:179], off
	global_load_dwordx4 v[92:95], v[178:179], off offset:-16
	ds_read_b64 v[122:123], v218 offset:10240
	v_lshl_add_u64 v[178:179], v[178:179], 0, s[88:89]
	s_waitcnt lgkmcnt(0)
	v_pk_add_f32 v[116:117], v[116:117], v[122:123] op_sel_hi:[1,0] neg_lo:[0,1] neg_hi:[0,1]
	s_nop 0
	v_pk_mul_f32 v[124:125], v[122:123], v[116:117] op_sel:[1,0]
	v_pk_add_f32 v[118:119], v[118:119], v[122:123] op_sel_hi:[1,0] neg_lo:[0,1] neg_hi:[0,1]
	s_waitcnt vmcnt(0)
	v_mov_b32_e32 v116, v92
	v_mov_b32_e32 v117, v94
	v_pk_mul_f32 v[124:125], v[116:117], v[124:125]
	v_pk_mul_f32 v[118:119], v[122:123], v[118:119] op_sel:[1,0]
	v_mov_b32_e32 v94, v93
	v_pk_mul_f32 v[92:93], v[94:95], v[118:119]
	v_and_b32_sdwa v118, v125, v245 dst_sel:DWORD dst_unused:UNUSED_PAD src0_sel:WORD_1 src1_sel:DWORD
	v_and_b32_sdwa v119, v124, v245 dst_sel:DWORD dst_unused:UNUSED_PAD src0_sel:WORD_1 src1_sel:DWORD
	v_add3_u32 v124, v124, v119, s68
	v_add3_u32 v118, v125, v118, s68
	v_and_b32_sdwa v119, v93, v245 dst_sel:DWORD dst_unused:UNUSED_PAD src0_sel:WORD_1 src1_sel:DWORD
	v_and_b32_sdwa v125, v92, v245 dst_sel:DWORD dst_unused:UNUSED_PAD src0_sel:WORD_1 src1_sel:DWORD
	v_add3_u32 v93, v93, v119, s68
	v_add3_u32 v92, v92, v125, s68
	v_and_b32_e32 v93, 0xffff0000, v93
	v_and_b32_e32 v92, 0xffff0000, v92
	v_or_b32_sdwa v119, v93, v118 dst_sel:DWORD dst_unused:UNUSED_PAD src0_sel:DWORD src1_sel:WORD_1
	v_or_b32_sdwa v118, v92, v124 dst_sel:DWORD dst_unused:UNUSED_PAD src0_sel:DWORD src1_sel:WORD_1
	v_lshlrev_b32_e32 v93, 16, v121
	v_lshlrev_b32_e32 v92, 16, v120
	v_and_b32_e32 v121, 0xffff0000, v121
	v_and_b32_e32 v120, 0xffff0000, v120
	v_pk_add_f32 v[92:93], v[92:93], v[122:123] op_sel_hi:[1,0] neg_lo:[0,1] neg_hi:[0,1]
	v_pk_add_f32 v[120:121], v[120:121], v[122:123] op_sel_hi:[1,0] neg_lo:[0,1] neg_hi:[0,1]
	v_pk_mul_f32 v[124:125], v[122:123], v[92:93] op_sel:[1,0]
	v_mov_b32_e32 v93, v90
	v_pk_mul_f32 v[120:121], v[122:123], v[120:121] op_sel:[1,0]
	v_mov_b32_e32 v90, v89
	v_mov_b32_e32 v92, v88
	v_pk_mul_f32 v[88:89], v[90:91], v[120:121]
	v_pk_mul_f32 v[124:125], v[92:93], v[124:125]
	v_and_b32_sdwa v122, v89, v245 dst_sel:DWORD dst_unused:UNUSED_PAD src0_sel:WORD_1 src1_sel:DWORD
	v_and_b32_sdwa v123, v88, v245 dst_sel:DWORD dst_unused:UNUSED_PAD src0_sel:WORD_1 src1_sel:DWORD
	v_and_b32_sdwa v120, v125, v245 dst_sel:DWORD dst_unused:UNUSED_PAD src0_sel:WORD_1 src1_sel:DWORD
	v_and_b32_sdwa v121, v124, v245 dst_sel:DWORD dst_unused:UNUSED_PAD src0_sel:WORD_1 src1_sel:DWORD
	v_add3_u32 v89, v89, v122, s68
	v_add3_u32 v88, v88, v123, s68
	v_add3_u32 v121, v124, v121, s68
	v_add3_u32 v120, v125, v120, s68
	v_and_b32_e32 v89, 0xffff0000, v89
	v_and_b32_e32 v88, 0xffff0000, v88
	v_or_b32_sdwa v89, v89, v120 dst_sel:DWORD dst_unused:UNUSED_PAD src0_sel:DWORD src1_sel:WORD_1
	v_or_b32_sdwa v88, v88, v121 dst_sel:DWORD dst_unused:UNUSED_PAD src0_sel:DWORD src1_sel:WORD_1
	ds_write2_b64 v219, v[118:119], v[88:89] offset1:4
	ds_read_b64 v[88:89], v218 offset:10368
	v_lshlrev_b32_e32 v119, 16, v113
	v_lshlrev_b32_e32 v118, 16, v112
	v_and_b32_e32 v113, 0xffff0000, v113
	v_and_b32_e32 v112, 0xffff0000, v112
	s_waitcnt lgkmcnt(0)
; #define LAS __attribute__((address_space(3)))
; __device__ __forceinline__ unsigned pk2(float lo, float hi) { return f2bf(lo) | (f2bf(hi) << 16); }
; __device__ __forceinline__ float bflo(unsigned w) { return __uint_as_float(w << 16); }
; __device__ __forceinline__ float bfhi(unsigned w) { return __uint_as_float(w & 0xffff0000u); }
; __device__ __forceinline__ void sgu_item(LAS unsigned char* wl, const bf16* proj, bf16* ymix, const float* vstat, const float* sgu_g, const bf16* Wm, const float* sgu_b, int chunk, int h, int lane) {
;     ...
;         for (int i = 0; i < 8; ++i) { const int s = rsub + 16 * i; const f32x2 ms = st[s]; const v4u w = raw[i];
;             v2u lo, hi; lo.x = pk2((bflo(w.x) - ms.x) * ms.y * g0[0], (bfhi(w.x) - ms.x) * ms.y * g0[1]); lo.y = pk2((bflo(w.y) - ms.x) * ms.y * g0[2], (bfhi(w.y) - ms.x) * ms.y * g0[3]);
;             hi.x = pk2((bflo(w.z) - ms.x) * ms.y * g1[0], (bfhi(w.z) - ms.x) * ms.y * g1[1]); hi.y = pk2((bflo(w.w) - ms.x) * ms.y * g1[2], (bfhi(w.w) - ms.x) * ms.y * g1[3]);
;             *(LAS v2u*)(wl + s * VP2 + (4 * c16) * 2) = lo; *(LAS v2u*)(wl + s * VP2 + (16 + 4 * c16) * 2) = hi; }
	v_pk_add_f32 v[118:119], v[118:119], v[88:89] op_sel_hi:[1,0] neg_lo:[0,1] neg_hi:[0,1]
	v_pk_add_f32 v[112:113], v[112:113], v[88:89] op_sel_hi:[1,0] neg_lo:[0,1] neg_hi:[0,1]
	v_pk_mul_f32 v[118:119], v[88:89], v[118:119] op_sel:[1,0]
	v_pk_mul_f32 v[112:113], v[88:89], v[112:113] op_sel:[1,0]
	v_pk_mul_f32 v[118:119], v[116:117], v[118:119]
	v_pk_mul_f32 v[112:113], v[94:95], v[112:113]
	v_and_b32_sdwa v120, v119, v245 dst_sel:DWORD dst_unused:UNUSED_PAD src0_sel:WORD_1 src1_sel:DWORD
	v_and_b32_sdwa v121, v118, v245 dst_sel:DWORD dst_unused:UNUSED_PAD src0_sel:WORD_1 src1_sel:DWORD
	v_add3_u32 v118, v118, v121, s68
	v_add3_u32 v119, v119, v120, s68
	v_and_b32_sdwa v120, v113, v245 dst_sel:DWORD dst_unused:UNUSED_PAD src0_sel:WORD_1 src1_sel:DWORD
	v_and_b32_sdwa v121, v112, v245 dst_sel:DWORD dst_unused:UNUSED_PAD src0_sel:WORD_1 src1_sel:DWORD
	v_add3_u32 v113, v113, v120, s68
	v_add3_u32 v112, v112, v121, s68
	v_and_b32_e32 v113, 0xffff0000, v113
	v_and_b32_e32 v112, 0xffff0000, v112
	v_or_b32_sdwa v113, v113, v119 dst_sel:DWORD dst_unused:UNUSED_PAD src0_sel:DWORD src1_sel:WORD_1
	v_or_b32_sdwa v112, v112, v118 dst_sel:DWORD dst_unused:UNUSED_PAD src0_sel:DWORD src1_sel:WORD_1
	v_lshlrev_b32_e32 v119, 16, v115
	v_lshlrev_b32_e32 v118, 16, v114
	v_pk_add_f32 v[118:119], v[118:119], v[88:89] op_sel_hi:[1,0] neg_lo:[0,1] neg_hi:[0,1]
	v_and_b32_e32 v115, 0xffff0000, v115
	v_and_b32_e32 v114, 0xffff0000, v114
	v_pk_mul_f32 v[118:119], v[88:89], v[118:119] op_sel:[1,0]
	v_pk_add_f32 v[114:115], v[114:115], v[88:89] op_sel_hi:[1,0] neg_lo:[0,1] neg_hi:[0,1]
	v_pk_mul_f32 v[118:119], v[92:93], v[118:119]
	v_pk_mul_f32 v[88:89], v[88:89], v[114:115] op_sel:[1,0]
	v_and_b32_sdwa v114, v119, v245 dst_sel:DWORD dst_unused:UNUSED_PAD src0_sel:WORD_1 src1_sel:DWORD
	v_pk_mul_f32 v[88:89], v[90:91], v[88:89]
	v_and_b32_sdwa v115, v118, v245 dst_sel:DWORD dst_unused:UNUSED_PAD src0_sel:WORD_1 src1_sel:DWORD
	v_add3_u32 v115, v118, v115, s68
	v_add3_u32 v114, v119, v114, s68
	v_and_b32_sdwa v118, v89, v245 dst_sel:DWORD dst_unused:UNUSED_PAD src0_sel:WORD_1 src1_sel:DWORD
	v_and_b32_sdwa v119, v88, v245 dst_sel:DWORD dst_unused:UNUSED_PAD src0_sel:WORD_1 src1_sel:DWORD
	v_add3_u32 v89, v89, v118, s68
	v_add3_u32 v88, v88, v119, s68
	v_and_b32_e32 v89, 0xffff0000, v89
	v_and_b32_e32 v88, 0xffff0000, v88
	v_or_b32_sdwa v89, v89, v114 dst_sel:DWORD dst_unused:UNUSED_PAD src0_sel:DWORD src1_sel:WORD_1
	v_or_b32_sdwa v88, v88, v115 dst_sel:DWORD dst_unused:UNUSED_PAD src0_sel:DWORD src1_sel:WORD_1
	ds_write2_b64 v219, v[112:113], v[88:89] offset0:160 offset1:164
	ds_read_b64 v[112:113], v218 offset:10496
	v_lshlrev_b32_e32 v89, 16, v109
	v_lshlrev_b32_e32 v88, 16, v108
	v_and_b32_e32 v109, 0xffff0000, v109
	v_and_b32_e32 v108, 0xffff0000, v108
	s_waitcnt lgkmcnt(0)
	v_pk_add_f32 v[88:89], v[88:89], v[112:113] op_sel_hi:[1,0] neg_lo:[0,1] neg_hi:[0,1]
	v_pk_add_f32 v[108:109], v[108:109], v[112:113] op_sel_hi:[1,0] neg_lo:[0,1] neg_hi:[0,1]
	v_pk_mul_f32 v[88:89], v[112:113], v[88:89] op_sel:[1,0]
	v_pk_mul_f32 v[108:109], v[112:113], v[108:109] op_sel:[1,0]
	v_pk_mul_f32 v[88:89], v[116:117], v[88:89]
	v_pk_mul_f32 v[108:109], v[94:95], v[108:109]
	v_and_b32_sdwa v114, v89, v245 dst_sel:DWORD dst_unused:UNUSED_PAD src0_sel:WORD_1 src1_sel:DWORD
	v_and_b32_sdwa v115, v88, v245 dst_sel:DWORD dst_unused:UNUSED_PAD src0_sel:WORD_1 src1_sel:DWORD
	v_add3_u32 v88, v88, v115, s68
	v_add3_u32 v89, v89, v114, s68
	v_and_b32_sdwa v114, v109, v245 dst_sel:DWORD dst_unused:UNUSED_PAD src0_sel:WORD_1 src1_sel:DWORD
	v_and_b32_sdwa v115, v108, v245 dst_sel:DWORD dst_unused:UNUSED_PAD src0_sel:WORD_1 src1_sel:DWORD
	v_add3_u32 v109, v109, v114, s68
	v_add3_u32 v108, v108, v115, s68
	v_and_b32_e32 v109, 0xffff0000, v109
	v_and_b32_e32 v108, 0xffff0000, v108
	v_or_b32_sdwa v89, v109, v89 dst_sel:DWORD dst_unused:UNUSED_PAD src0_sel:DWORD src1_sel:WORD_1
	v_or_b32_sdwa v88, v108, v88 dst_sel:DWORD dst_unused:UNUSED_PAD src0_sel:DWORD src1_sel:WORD_1
	v_lshlrev_b32_e32 v109, 16, v111
	v_lshlrev_b32_e32 v108, 16, v110
	v_pk_add_f32 v[108:109], v[108:109], v[112:113] op_sel_hi:[1,0] neg_lo:[0,1] neg_hi:[0,1]
	v_and_b32_e32 v111, 0xffff0000, v111
	v_and_b32_e32 v110, 0xffff0000, v110
	v_pk_mul_f32 v[108:109], v[112:113], v[108:109] op_sel:[1,0]
	v_pk_add_f32 v[110:111], v[110:111], v[112:113] op_sel_hi:[1,0] neg_lo:[0,1] neg_hi:[0,1]
	v_pk_mul_f32 v[108:109], v[92:93], v[108:109]
	v_pk_mul_f32 v[110:111], v[112:113], v[110:111] op_sel:[1,0]
	v_and_b32_sdwa v112, v109, v245 dst_sel:DWORD dst_unused:UNUSED_PAD src0_sel:WORD_1 src1_sel:DWORD
	v_pk_mul_f32 v[110:111], v[90:91], v[110:111]
	v_and_b32_sdwa v113, v108, v245 dst_sel:DWORD dst_unused:UNUSED_PAD src0_sel:WORD_1 src1_sel:DWORD
	v_add3_u32 v108, v108, v113, s68
	v_add3_u32 v109, v109, v112, s68
	v_and_b32_sdwa v112, v111, v245 dst_sel:DWORD dst_unused:UNUSED_PAD src0_sel:WORD_1 src1_sel:DWORD
	v_and_b32_sdwa v113, v110, v245 dst_sel:DWORD dst_unused:UNUSED_PAD src0_sel:WORD_1 src1_sel:DWORD
	v_add3_u32 v111, v111, v112, s68
	v_add3_u32 v110, v110, v113, s68
	v_and_b32_e32 v111, 0xffff0000, v111
	v_and_b32_e32 v110, 0xffff0000, v110
	v_or_b32_sdwa v109, v111, v109 dst_sel:DWORD dst_unused:UNUSED_PAD src0_sel:DWORD src1_sel:WORD_1
	v_or_b32_sdwa v108, v110, v108 dst_sel:DWORD dst_unused:UNUSED_PAD src0_sel:DWORD src1_sel:WORD_1
	v_add_u32_e32 v110, 0x800, v219
	ds_write2_b64 v110, v[88:89], v[108:109] offset0:64 offset1:68
	ds_read_b64 v[88:89], v218 offset:10624
	v_lshlrev_b32_e32 v109, 16, v105
	v_lshlrev_b32_e32 v108, 16, v104
	v_and_b32_e32 v105, 0xffff0000, v105
	v_and_b32_e32 v104, 0xffff0000, v104
	s_waitcnt lgkmcnt(0)
; #define LAS __attribute__((address_space(3)))
; __device__ __forceinline__ unsigned pk2(float lo, float hi) { return f2bf(lo) | (f2bf(hi) << 16); }
; __device__ __forceinline__ float bflo(unsigned w) { return __uint_as_float(w << 16); }
; __device__ __forceinline__ float bfhi(unsigned w) { return __uint_as_float(w & 0xffff0000u); }
; __device__ __forceinline__ void sgu_item(LAS unsigned char* wl, const bf16* proj, bf16* ymix, const float* vstat, const float* sgu_g, const bf16* Wm, const float* sgu_b, int chunk, int h, int lane) {
;     ...
;         for (int i = 0; i < 8; ++i) { const int s = rsub + 16 * i; const f32x2 ms = st[s]; const v4u w = raw[i];
;             v2u lo, hi; lo.x = pk2((bflo(w.x) - ms.x) * ms.y * g0[0], (bfhi(w.x) - ms.x) * ms.y * g0[1]); lo.y = pk2((bflo(w.y) - ms.x) * ms.y * g0[2], (bfhi(w.y) - ms.x) * ms.y * g0[3]);
;             hi.x = pk2((bflo(w.z) - ms.x) * ms.y * g1[0], (bfhi(w.z) - ms.x) * ms.y * g1[1]); hi.y = pk2((bflo(w.w) - ms.x) * ms.y * g1[2], (bfhi(w.w) - ms.x) * ms.y * g1[3]);
;             *(LAS v2u*)(wl + s * VP2 + (4 * c16) * 2) = lo; *(LAS v2u*)(wl + s * VP2 + (16 + 4 * c16) * 2) = hi; }
	v_pk_add_f32 v[108:109], v[108:109], v[88:89] op_sel_hi:[1,0] neg_lo:[0,1] neg_hi:[0,1]
	v_pk_add_f32 v[104:105], v[104:105], v[88:89] op_sel_hi:[1,0] neg_lo:[0,1] neg_hi:[0,1]
	v_pk_mul_f32 v[108:109], v[88:89], v[108:109] op_sel:[1,0]
	v_pk_mul_f32 v[104:105], v[88:89], v[104:105] op_sel:[1,0]
	v_pk_mul_f32 v[108:109], v[116:117], v[108:109]
	v_pk_mul_f32 v[104:105], v[94:95], v[104:105]
	v_and_b32_sdwa v111, v109, v245 dst_sel:DWORD dst_unused:UNUSED_PAD src0_sel:WORD_1 src1_sel:DWORD
	v_and_b32_sdwa v112, v108, v245 dst_sel:DWORD dst_unused:UNUSED_PAD src0_sel:WORD_1 src1_sel:DWORD
	v_add3_u32 v108, v108, v112, s68
	v_add3_u32 v109, v109, v111, s68
	v_and_b32_sdwa v111, v105, v245 dst_sel:DWORD dst_unused:UNUSED_PAD src0_sel:WORD_1 src1_sel:DWORD
	v_and_b32_sdwa v112, v104, v245 dst_sel:DWORD dst_unused:UNUSED_PAD src0_sel:WORD_1 src1_sel:DWORD
	v_add3_u32 v105, v105, v111, s68
	v_add3_u32 v104, v104, v112, s68
	v_and_b32_e32 v105, 0xffff0000, v105
	v_and_b32_e32 v104, 0xffff0000, v104
	v_or_b32_sdwa v105, v105, v109 dst_sel:DWORD dst_unused:UNUSED_PAD src0_sel:DWORD src1_sel:WORD_1
	v_or_b32_sdwa v104, v104, v108 dst_sel:DWORD dst_unused:UNUSED_PAD src0_sel:DWORD src1_sel:WORD_1
	v_lshlrev_b32_e32 v109, 16, v107
	v_lshlrev_b32_e32 v108, 16, v106
	v_pk_add_f32 v[108:109], v[108:109], v[88:89] op_sel_hi:[1,0] neg_lo:[0,1] neg_hi:[0,1]
	v_and_b32_e32 v107, 0xffff0000, v107
	v_and_b32_e32 v106, 0xffff0000, v106
	v_pk_mul_f32 v[108:109], v[88:89], v[108:109] op_sel:[1,0]
	v_pk_add_f32 v[106:107], v[106:107], v[88:89] op_sel_hi:[1,0] neg_lo:[0,1] neg_hi:[0,1]
	v_pk_mul_f32 v[108:109], v[92:93], v[108:109]
	v_pk_mul_f32 v[88:89], v[88:89], v[106:107] op_sel:[1,0]
	v_and_b32_sdwa v106, v109, v245 dst_sel:DWORD dst_unused:UNUSED_PAD src0_sel:WORD_1 src1_sel:DWORD
	v_pk_mul_f32 v[88:89], v[90:91], v[88:89]
	v_and_b32_sdwa v107, v108, v245 dst_sel:DWORD dst_unused:UNUSED_PAD src0_sel:WORD_1 src1_sel:DWORD
	v_add3_u32 v107, v108, v107, s68
	v_add3_u32 v106, v109, v106, s68
	v_and_b32_sdwa v108, v89, v245 dst_sel:DWORD dst_unused:UNUSED_PAD src0_sel:WORD_1 src1_sel:DWORD
	v_and_b32_sdwa v109, v88, v245 dst_sel:DWORD dst_unused:UNUSED_PAD src0_sel:WORD_1 src1_sel:DWORD
	v_add3_u32 v89, v89, v108, s68
	v_add3_u32 v88, v88, v109, s68
	v_and_b32_e32 v89, 0xffff0000, v89
	v_and_b32_e32 v88, 0xffff0000, v88
	v_or_b32_sdwa v89, v89, v106 dst_sel:DWORD dst_unused:UNUSED_PAD src0_sel:DWORD src1_sel:WORD_1
	v_or_b32_sdwa v88, v88, v107 dst_sel:DWORD dst_unused:UNUSED_PAD src0_sel:DWORD src1_sel:WORD_1
	ds_write2_b64 v110, v[104:105], v[88:89] offset0:224 offset1:228
	ds_read_b64 v[104:105], v218 offset:10752
	v_lshlrev_b32_e32 v89, 16, v101
	v_lshlrev_b32_e32 v88, 16, v100
	v_and_b32_e32 v101, 0xffff0000, v101
	v_and_b32_e32 v100, 0xffff0000, v100
	s_waitcnt lgkmcnt(0)
	v_pk_add_f32 v[88:89], v[88:89], v[104:105] op_sel_hi:[1,0] neg_lo:[0,1] neg_hi:[0,1]
	v_pk_add_f32 v[100:101], v[100:101], v[104:105] op_sel_hi:[1,0] neg_lo:[0,1] neg_hi:[0,1]
	v_pk_mul_f32 v[88:89], v[104:105], v[88:89] op_sel:[1,0]
	v_pk_mul_f32 v[100:101], v[104:105], v[100:101] op_sel:[1,0]
	v_pk_mul_f32 v[88:89], v[116:117], v[88:89]
	v_pk_mul_f32 v[100:101], v[94:95], v[100:101]
	v_and_b32_sdwa v106, v89, v245 dst_sel:DWORD dst_unused:UNUSED_PAD src0_sel:WORD_1 src1_sel:DWORD
	v_and_b32_sdwa v107, v88, v245 dst_sel:DWORD dst_unused:UNUSED_PAD src0_sel:WORD_1 src1_sel:DWORD
	v_add3_u32 v88, v88, v107, s68
	v_add3_u32 v89, v89, v106, s68
	v_and_b32_sdwa v106, v101, v245 dst_sel:DWORD dst_unused:UNUSED_PAD src0_sel:WORD_1 src1_sel:DWORD
	v_and_b32_sdwa v107, v100, v245 dst_sel:DWORD dst_unused:UNUSED_PAD src0_sel:WORD_1 src1_sel:DWORD
	v_add3_u32 v101, v101, v106, s68
	v_add3_u32 v100, v100, v107, s68
	v_and_b32_e32 v101, 0xffff0000, v101
	v_and_b32_e32 v100, 0xffff0000, v100
	v_or_b32_sdwa v89, v101, v89 dst_sel:DWORD dst_unused:UNUSED_PAD src0_sel:DWORD src1_sel:WORD_1
	v_or_b32_sdwa v88, v100, v88 dst_sel:DWORD dst_unused:UNUSED_PAD src0_sel:DWORD src1_sel:WORD_1
	v_lshlrev_b32_e32 v101, 16, v103
	v_lshlrev_b32_e32 v100, 16, v102
	v_pk_add_f32 v[100:101], v[100:101], v[104:105] op_sel_hi:[1,0] neg_lo:[0,1] neg_hi:[0,1]
	v_and_b32_e32 v103, 0xffff0000, v103
	v_and_b32_e32 v102, 0xffff0000, v102
	v_pk_mul_f32 v[100:101], v[104:105], v[100:101] op_sel:[1,0]
	v_pk_add_f32 v[102:103], v[102:103], v[104:105] op_sel_hi:[1,0] neg_lo:[0,1] neg_hi:[0,1]
	v_pk_mul_f32 v[100:101], v[92:93], v[100:101]
	v_pk_mul_f32 v[102:103], v[104:105], v[102:103] op_sel:[1,0]
	v_and_b32_sdwa v104, v101, v245 dst_sel:DWORD dst_unused:UNUSED_PAD src0_sel:WORD_1 src1_sel:DWORD
	v_pk_mul_f32 v[102:103], v[90:91], v[102:103]
	v_and_b32_sdwa v105, v100, v245 dst_sel:DWORD dst_unused:UNUSED_PAD src0_sel:WORD_1 src1_sel:DWORD
	v_add3_u32 v100, v100, v105, s68
	v_add3_u32 v101, v101, v104, s68
	v_and_b32_sdwa v104, v103, v245 dst_sel:DWORD dst_unused:UNUSED_PAD src0_sel:WORD_1 src1_sel:DWORD
	v_and_b32_sdwa v105, v102, v245 dst_sel:DWORD dst_unused:UNUSED_PAD src0_sel:WORD_1 src1_sel:DWORD
	v_add3_u32 v103, v103, v104, s68
	v_add3_u32 v102, v102, v105, s68
	v_and_b32_e32 v103, 0xffff0000, v103
	v_and_b32_e32 v102, 0xffff0000, v102
	v_or_b32_sdwa v101, v103, v101 dst_sel:DWORD dst_unused:UNUSED_PAD src0_sel:DWORD src1_sel:WORD_1
	v_or_b32_sdwa v100, v102, v100 dst_sel:DWORD dst_unused:UNUSED_PAD src0_sel:DWORD src1_sel:WORD_1
	v_add_u32_e32 v102, 0x1000, v219
	ds_write2_b64 v102, v[88:89], v[100:101] offset0:128 offset1:132
	ds_read_b64 v[88:89], v218 offset:10880
	v_lshlrev_b32_e32 v101, 16, v97
	v_lshlrev_b32_e32 v100, 16, v96
	v_and_b32_e32 v97, 0xffff0000, v97
	v_and_b32_e32 v96, 0xffff0000, v96
	s_waitcnt lgkmcnt(0)
; #define LAS __attribute__((address_space(3)))
; __device__ __forceinline__ unsigned pk2(float lo, float hi) { return f2bf(lo) | (f2bf(hi) << 16); }
; __device__ __forceinline__ float bflo(unsigned w) { return __uint_as_float(w << 16); }
; __device__ __forceinline__ float bfhi(unsigned w) { return __uint_as_float(w & 0xffff0000u); }
; __device__ __forceinline__ void sgu_item(LAS unsigned char* wl, const bf16* proj, bf16* ymix, const float* vstat, const float* sgu_g, const bf16* Wm, const float* sgu_b, int chunk, int h, int lane) {
;     ...
;         for (int i = 0; i < 8; ++i) { const int s = rsub + 16 * i; const f32x2 ms = st[s]; const v4u w = raw[i];
;             v2u lo, hi; lo.x = pk2((bflo(w.x) - ms.x) * ms.y * g0[0], (bfhi(w.x) - ms.x) * ms.y * g0[1]); lo.y = pk2((bflo(w.y) - ms.x) * ms.y * g0[2], (bfhi(w.y) - ms.x) * ms.y * g0[3]);
;             hi.x = pk2((bflo(w.z) - ms.x) * ms.y * g1[0], (bfhi(w.z) - ms.x) * ms.y * g1[1]); hi.y = pk2((bflo(w.w) - ms.x) * ms.y * g1[2], (bfhi(w.w) - ms.x) * ms.y * g1[3]);
;             *(LAS v2u*)(wl + s * VP2 + (4 * c16) * 2) = lo; *(LAS v2u*)(wl + s * VP2 + (16 + 4 * c16) * 2) = hi; }
	v_pk_add_f32 v[100:101], v[100:101], v[88:89] op_sel_hi:[1,0] neg_lo:[0,1] neg_hi:[0,1]
	v_pk_add_f32 v[96:97], v[96:97], v[88:89] op_sel_hi:[1,0] neg_lo:[0,1] neg_hi:[0,1]
	v_pk_mul_f32 v[100:101], v[88:89], v[100:101] op_sel:[1,0]
	v_pk_mul_f32 v[96:97], v[88:89], v[96:97] op_sel:[1,0]
	v_pk_mul_f32 v[100:101], v[116:117], v[100:101]
	v_pk_mul_f32 v[96:97], v[94:95], v[96:97]
	v_and_b32_sdwa v102, v101, v245 dst_sel:DWORD dst_unused:UNUSED_PAD src0_sel:WORD_1 src1_sel:DWORD
	v_and_b32_sdwa v103, v100, v245 dst_sel:DWORD dst_unused:UNUSED_PAD src0_sel:WORD_1 src1_sel:DWORD
	v_add3_u32 v100, v100, v103, s68
	v_add3_u32 v101, v101, v102, s68
	v_and_b32_sdwa v102, v97, v245 dst_sel:DWORD dst_unused:UNUSED_PAD src0_sel:WORD_1 src1_sel:DWORD
	v_and_b32_sdwa v103, v96, v245 dst_sel:DWORD dst_unused:UNUSED_PAD src0_sel:WORD_1 src1_sel:DWORD
	v_add3_u32 v97, v97, v102, s68
	v_add3_u32 v96, v96, v103, s68
	v_and_b32_e32 v97, 0xffff0000, v97
	v_and_b32_e32 v96, 0xffff0000, v96
	v_or_b32_sdwa v97, v97, v101 dst_sel:DWORD dst_unused:UNUSED_PAD src0_sel:DWORD src1_sel:WORD_1
	v_or_b32_sdwa v96, v96, v100 dst_sel:DWORD dst_unused:UNUSED_PAD src0_sel:DWORD src1_sel:WORD_1
	v_lshlrev_b32_e32 v101, 16, v99
	v_lshlrev_b32_e32 v100, 16, v98
	v_pk_add_f32 v[100:101], v[100:101], v[88:89] op_sel_hi:[1,0] neg_lo:[0,1] neg_hi:[0,1]
	v_and_b32_e32 v99, 0xffff0000, v99
	v_and_b32_e32 v98, 0xffff0000, v98
	v_pk_mul_f32 v[100:101], v[88:89], v[100:101] op_sel:[1,0]
	v_pk_add_f32 v[98:99], v[98:99], v[88:89] op_sel_hi:[1,0] neg_lo:[0,1] neg_hi:[0,1]
	v_pk_mul_f32 v[100:101], v[92:93], v[100:101]
	v_pk_mul_f32 v[88:89], v[88:89], v[98:99] op_sel:[1,0]
	v_and_b32_sdwa v98, v101, v245 dst_sel:DWORD dst_unused:UNUSED_PAD src0_sel:WORD_1 src1_sel:DWORD
	v_pk_mul_f32 v[88:89], v[90:91], v[88:89]
	v_and_b32_sdwa v99, v100, v245 dst_sel:DWORD dst_unused:UNUSED_PAD src0_sel:WORD_1 src1_sel:DWORD
	v_add3_u32 v99, v100, v99, s68
	v_add3_u32 v98, v101, v98, s68
	v_and_b32_sdwa v100, v89, v245 dst_sel:DWORD dst_unused:UNUSED_PAD src0_sel:WORD_1 src1_sel:DWORD
	v_and_b32_sdwa v101, v88, v245 dst_sel:DWORD dst_unused:UNUSED_PAD src0_sel:WORD_1 src1_sel:DWORD
	v_add3_u32 v89, v89, v100, s68
	v_add3_u32 v88, v88, v101, s68
	v_and_b32_e32 v89, 0xffff0000, v89
	v_and_b32_e32 v88, 0xffff0000, v88
	v_or_b32_sdwa v89, v89, v98 dst_sel:DWORD dst_unused:UNUSED_PAD src0_sel:DWORD src1_sel:WORD_1
	v_or_b32_sdwa v88, v88, v99 dst_sel:DWORD dst_unused:UNUSED_PAD src0_sel:DWORD src1_sel:WORD_1
	v_add_u32_e32 v98, 0x1800, v219
	ds_write2_b64 v98, v[96:97], v[88:89] offset0:32 offset1:36
	ds_read_b64 v[88:89], v218 offset:11008
	v_lshlrev_b32_e32 v97, 16, v85
	v_lshlrev_b32_e32 v96, 16, v84
	v_and_b32_e32 v85, 0xffff0000, v85
	v_and_b32_e32 v84, 0xffff0000, v84
	s_waitcnt lgkmcnt(0)
	v_pk_add_f32 v[96:97], v[96:97], v[88:89] op_sel_hi:[1,0] neg_lo:[0,1] neg_hi:[0,1]
	v_pk_add_f32 v[84:85], v[84:85], v[88:89] op_sel_hi:[1,0] neg_lo:[0,1] neg_hi:[0,1]
	v_pk_mul_f32 v[96:97], v[88:89], v[96:97] op_sel:[1,0]
	v_pk_mul_f32 v[84:85], v[88:89], v[84:85] op_sel:[1,0]
	v_pk_mul_f32 v[96:97], v[116:117], v[96:97]
	v_pk_mul_f32 v[84:85], v[94:95], v[84:85]
	v_and_b32_sdwa v99, v97, v245 dst_sel:DWORD dst_unused:UNUSED_PAD src0_sel:WORD_1 src1_sel:DWORD
	v_and_b32_sdwa v100, v96, v245 dst_sel:DWORD dst_unused:UNUSED_PAD src0_sel:WORD_1 src1_sel:DWORD
	v_add3_u32 v96, v96, v100, s68
	v_add3_u32 v97, v97, v99, s68
	v_and_b32_sdwa v99, v85, v245 dst_sel:DWORD dst_unused:UNUSED_PAD src0_sel:WORD_1 src1_sel:DWORD
	v_and_b32_sdwa v100, v84, v245 dst_sel:DWORD dst_unused:UNUSED_PAD src0_sel:WORD_1 src1_sel:DWORD
	v_add3_u32 v85, v85, v99, s68
	v_add3_u32 v84, v84, v100, s68
	v_and_b32_e32 v85, 0xffff0000, v85
	v_and_b32_e32 v84, 0xffff0000, v84
	v_or_b32_sdwa v85, v85, v97 dst_sel:DWORD dst_unused:UNUSED_PAD src0_sel:DWORD src1_sel:WORD_1
	v_or_b32_sdwa v84, v84, v96 dst_sel:DWORD dst_unused:UNUSED_PAD src0_sel:DWORD src1_sel:WORD_1
	v_lshlrev_b32_e32 v97, 16, v87
	v_lshlrev_b32_e32 v96, 16, v86
	v_pk_add_f32 v[96:97], v[96:97], v[88:89] op_sel_hi:[1,0] neg_lo:[0,1] neg_hi:[0,1]
	v_and_b32_e32 v87, 0xffff0000, v87
	v_and_b32_e32 v86, 0xffff0000, v86
	v_pk_mul_f32 v[96:97], v[88:89], v[96:97] op_sel:[1,0]
	v_pk_add_f32 v[86:87], v[86:87], v[88:89] op_sel_hi:[1,0] neg_lo:[0,1] neg_hi:[0,1]
	v_pk_mul_f32 v[96:97], v[92:93], v[96:97]
	v_pk_mul_f32 v[86:87], v[88:89], v[86:87] op_sel:[1,0]
	v_and_b32_sdwa v88, v97, v245 dst_sel:DWORD dst_unused:UNUSED_PAD src0_sel:WORD_1 src1_sel:DWORD
	v_pk_mul_f32 v[86:87], v[90:91], v[86:87]
	v_and_b32_sdwa v89, v96, v245 dst_sel:DWORD dst_unused:UNUSED_PAD src0_sel:WORD_1 src1_sel:DWORD
	v_add3_u32 v89, v96, v89, s68
	v_add3_u32 v88, v97, v88, s68
	v_and_b32_sdwa v96, v87, v245 dst_sel:DWORD dst_unused:UNUSED_PAD src0_sel:WORD_1 src1_sel:DWORD
	v_and_b32_sdwa v97, v86, v245 dst_sel:DWORD dst_unused:UNUSED_PAD src0_sel:WORD_1 src1_sel:DWORD
	v_add3_u32 v87, v87, v96, s68
	v_add3_u32 v86, v86, v97, s68
	v_and_b32_e32 v87, 0xffff0000, v87
	v_and_b32_e32 v86, 0xffff0000, v86
	v_or_b32_sdwa v87, v87, v88 dst_sel:DWORD dst_unused:UNUSED_PAD src0_sel:DWORD src1_sel:WORD_1
	v_or_b32_sdwa v86, v86, v89 dst_sel:DWORD dst_unused:UNUSED_PAD src0_sel:DWORD src1_sel:WORD_1
	ds_write2_b64 v98, v[84:85], v[86:87] offset0:192 offset1:196
	ds_read_b64 v[84:85], v218 offset:11136
	v_lshlrev_b32_e32 v87, 16, v81
	v_lshlrev_b32_e32 v86, 16, v80
	v_and_b32_e32 v81, 0xffff0000, v81
	v_and_b32_e32 v80, 0xffff0000, v80
	s_waitcnt lgkmcnt(0)
; #define LAS __attribute__((address_space(3)))
; #define MFMA16(a, b, c) __builtin_amdgcn_mfma_f32_16x16x32_bf16((a), (b), (c), 0, 0, 0)
; __device__ __forceinline__ unsigned pk2(float lo, float hi) { return f2bf(lo) | (f2bf(hi) << 16); }
; __device__ __forceinline__ float bflo(unsigned w) { return __uint_as_float(w << 16); }
; __device__ __forceinline__ float bfhi(unsigned w) { return __uint_as_float(w & 0xffff0000u); }
; #define LDS_WAIT() asm volatile("s_waitcnt lgkmcnt(0)" ::: "memory")
; __device__ __forceinline__ void sgu_item(LAS unsigned char* wl, const bf16* proj, bf16* ymix, const float* vstat, const float* sgu_g, const bf16* Wm, const float* sgu_b, int chunk, int h, int lane) {
;     ...
;         for (int i = 0; i < 8; ++i) { const int s = rsub + 16 * i; const f32x2 ms = st[s]; const v4u w = raw[i];
;             v2u lo, hi; lo.x = pk2((bflo(w.x) - ms.x) * ms.y * g0[0], (bfhi(w.x) - ms.x) * ms.y * g0[1]); lo.y = pk2((bflo(w.y) - ms.x) * ms.y * g0[2], (bfhi(w.y) - ms.x) * ms.y * g0[3]);
;             hi.x = pk2((bflo(w.z) - ms.x) * ms.y * g1[0], (bfhi(w.z) - ms.x) * ms.y * g1[1]); hi.y = pk2((bflo(w.w) - ms.x) * ms.y * g1[2], (bfhi(w.w) - ms.x) * ms.y * g1[3]);
;             *(LAS v2u*)(wl + s * VP2 + (4 * c16) * 2) = lo; *(LAS v2u*)(wl + s * VP2 + (16 + 4 * c16) * 2) = hi; }
;         v4u uu8[8];
; #pragma unroll
;         for (int tb = 0; tb < 8; ++tb) uu8[tb] = __builtin_nontemporal_load((const v4u*)(proj + (R0 + 16 * tb + r) * DIN + 512 + colv + 8 * q));
;         LDS_WAIT();
;         v2u olo[8];
; #pragma unroll
;         for (int n = 0; n < 2; ++n) {
;             f32x4 z[8];
; #pragma unroll
;             for (int tb = 0; tb < 8; ++tb) z[tb] = (f32x4){0.f, 0.f, 0.f, 0.f};
;             int f = 0;
; #pragma unroll
;             for (int ks = 0; ks < 4; ++ks) {
;                 LAS unsigned char* ad = wl + (ks * 32 + 8 * q + (r >> 2)) * VP2 + (16 * n) * 2 + 8 * (r & 3);
;                 const s16x4 lo = __builtin_bit_cast(s16x4, __builtin_amdgcn_ds_read_tr16_b64_v4i16((LAS s16x4*)ad));
;                 const s16x4 hi = __builtin_bit_cast(s16x4, __builtin_amdgcn_ds_read_tr16_b64_v4i16((LAS s16x4*)(ad + 4 * VP2)));
;                 const bf16x8 vf = __builtin_shufflevector(lo, hi, 0, 1, 2, 3, 4, 5, 6, 7);
; #pragma unroll
;                 for (int tb = 2 * ks; tb < 8; ++tb) z[tb] = MFMA16(vf, wmf[f++], z[tb]);
	v_pk_add_f32 v[86:87], v[86:87], v[84:85] op_sel_hi:[1,0] neg_lo:[0,1] neg_hi:[0,1]
	v_pk_add_f32 v[80:81], v[80:81], v[84:85] op_sel_hi:[1,0] neg_lo:[0,1] neg_hi:[0,1]
	v_pk_mul_f32 v[86:87], v[84:85], v[86:87] op_sel:[1,0]
	v_pk_mul_f32 v[80:81], v[84:85], v[80:81] op_sel:[1,0]
	v_pk_mul_f32 v[86:87], v[116:117], v[86:87]
	v_pk_mul_f32 v[80:81], v[94:95], v[80:81]
	v_and_b32_sdwa v88, v87, v245 dst_sel:DWORD dst_unused:UNUSED_PAD src0_sel:WORD_1 src1_sel:DWORD
	v_and_b32_sdwa v89, v86, v245 dst_sel:DWORD dst_unused:UNUSED_PAD src0_sel:WORD_1 src1_sel:DWORD
	v_add3_u32 v86, v86, v89, s68
	v_add3_u32 v87, v87, v88, s68
	v_and_b32_sdwa v88, v81, v245 dst_sel:DWORD dst_unused:UNUSED_PAD src0_sel:WORD_1 src1_sel:DWORD
	v_and_b32_sdwa v89, v80, v245 dst_sel:DWORD dst_unused:UNUSED_PAD src0_sel:WORD_1 src1_sel:DWORD
	v_add3_u32 v81, v81, v88, s68
	v_add3_u32 v80, v80, v89, s68
	v_and_b32_e32 v81, 0xffff0000, v81
	v_and_b32_e32 v80, 0xffff0000, v80
	v_or_b32_sdwa v81, v81, v87 dst_sel:DWORD dst_unused:UNUSED_PAD src0_sel:DWORD src1_sel:WORD_1
	v_or_b32_sdwa v80, v80, v86 dst_sel:DWORD dst_unused:UNUSED_PAD src0_sel:DWORD src1_sel:WORD_1
	v_lshlrev_b32_e32 v87, 16, v83
	v_lshlrev_b32_e32 v86, 16, v82
	v_pk_add_f32 v[86:87], v[86:87], v[84:85] op_sel_hi:[1,0] neg_lo:[0,1] neg_hi:[0,1]
	v_and_b32_e32 v83, 0xffff0000, v83
	v_and_b32_e32 v82, 0xffff0000, v82
	v_pk_mul_f32 v[86:87], v[84:85], v[86:87] op_sel:[1,0]
	v_pk_add_f32 v[82:83], v[82:83], v[84:85] op_sel_hi:[1,0] neg_lo:[0,1] neg_hi:[0,1]
	v_pk_mul_f32 v[86:87], v[92:93], v[86:87]
	v_pk_mul_f32 v[82:83], v[84:85], v[82:83] op_sel:[1,0]
	v_and_b32_sdwa v84, v87, v245 dst_sel:DWORD dst_unused:UNUSED_PAD src0_sel:WORD_1 src1_sel:DWORD
	v_pk_mul_f32 v[82:83], v[90:91], v[82:83]
	v_and_b32_sdwa v85, v86, v245 dst_sel:DWORD dst_unused:UNUSED_PAD src0_sel:WORD_1 src1_sel:DWORD
	v_add3_u32 v85, v86, v85, s68
	v_add3_u32 v84, v87, v84, s68
	v_and_b32_sdwa v86, v83, v245 dst_sel:DWORD dst_unused:UNUSED_PAD src0_sel:WORD_1 src1_sel:DWORD
	v_and_b32_sdwa v87, v82, v245 dst_sel:DWORD dst_unused:UNUSED_PAD src0_sel:WORD_1 src1_sel:DWORD
	v_add3_u32 v83, v83, v86, s68
	v_add3_u32 v82, v82, v87, s68
	v_and_b32_e32 v83, 0xffff0000, v83
	v_and_b32_e32 v82, 0xffff0000, v82
	v_or_b32_sdwa v83, v83, v84 dst_sel:DWORD dst_unused:UNUSED_PAD src0_sel:DWORD src1_sel:WORD_1
	v_or_b32_sdwa v82, v82, v85 dst_sel:DWORD dst_unused:UNUSED_PAD src0_sel:DWORD src1_sel:WORD_1
	v_add_u32_e32 v84, 0x2000, v219
	ds_write2_b64 v84, v[80:81], v[82:83] offset0:96 offset1:100
	v_lshl_add_u64 v[80:81], v[188:189], 0, s[20:21]
	v_add_co_u32_e32 v82, vcc, s0, v80
	s_mov_b32 s0, 0xf10c000
	s_nop 0
	v_addc_co_u32_e32 v83, vcc, 0, v81, vcc
	global_load_dwordx4 v[104:107], v[82:83], off offset:1024
	v_add_co_u32_e32 v82, vcc, s0, v80
	s_mov_b32 s0, 0xf118000
	s_nop 0
	v_addc_co_u32_e32 v83, vcc, 0, v81, vcc
	global_load_dwordx4 v[100:103], v[82:83], off offset:1024
	v_add_co_u32_e32 v82, vcc, s0, v80
	s_mov_b32 s0, 0xf130000
	s_nop 0
	v_addc_co_u32_e32 v83, vcc, 0, v81, vcc
	global_load_dwordx4 v[96:99], v[82:83], off offset:1024
	v_lshl_add_u64 v[82:83], v[190:191], 0, s[20:21]
	global_load_dwordx4 v[92:95], v[82:83], off
	v_add_co_u32_e32 v82, vcc, s0, v80
	s_mov_b32 s0, 0xf13c000
	s_nop 0
	v_addc_co_u32_e32 v83, vcc, 0, v81, vcc
	global_load_dwordx4 v[88:91], v[82:83], off offset:1024
	v_add_co_u32_e32 v82, vcc, s0, v80
	s_mov_b32 s0, 0xf148000
	s_nop 0
	v_addc_co_u32_e32 v83, vcc, 0, v81, vcc
	global_load_dwordx4 v[84:87], v[82:83], off offset:1024
	v_add_co_u32_e32 v80, vcc, s0, v80
	v_lshl_add_u64 v[108:109], v[186:187], 0, s[20:21]
	s_nop 0
	v_addc_co_u32_e32 v81, vcc, 0, v81, vcc
	global_load_dwordx4 v[80:83], v[80:81], off offset:1024
	s_mov_b32 s0, 0x10900000
	global_load_dwordx4 v[108:111], v[108:109], off
	s_waitcnt lgkmcnt(0)
	ds_read_b64_tr_b16 v[116:117], v220 offset:320
	ds_read_b64_tr_b16 v[114:115], v220
	ds_read_b64_tr_b16 v[112:113], v220 offset:32
	ds_read_b64_tr_b16 v[208:209], v220 offset:2560
	ds_read_b64_tr_b16 v[210:211], v220 offset:2880
	s_waitcnt lgkmcnt(0)
	v_mfma_f32_16x16x32_bf16 v[118:121], v[114:117], v[0:3], 0
	v_mfma_f32_16x16x32_bf16 v[122:125], v[114:117], v[4:7], 0
	s_nop 6
	v_mov_b32_e32 v138, v119
	v_mov_b32_e32 v119, v120
	v_pk_add_f32 v[118:119], v[162:163], v[118:119]
	v_mfma_f32_16x16x32_bf16 v[126:129], v[114:117], v[8:11], 0
	v_mov_b32_e32 v139, v121
	v_pk_add_f32 v[138:139], v[162:163], v[138:139]
	v_mfma_f32_16x16x32_bf16 v[130:133], v[114:117], v[16:19], 0
	v_mfma_f32_16x16x32_bf16 v[134:137], v[114:117], v[24:27], 0
	v_mfma_f32_16x16x32_bf16 v[200:203], v[114:117], v[48:51], 0
	v_mfma_f32_16x16x32_bf16 v[204:207], v[114:117], v[32:35], 0
	v_mfma_f32_16x16x32_bf16 v[114:117], v[114:117], v[40:43], 0
	v_mfma_f32_16x16x32_bf16 v[126:129], v[208:211], v[12:15], v[126:129]
	v_mfma_f32_16x16x32_bf16 v[130:133], v[208:211], v[20:23], v[130:133]
	v_mfma_f32_16x16x32_bf16 v[134:137], v[208:211], v[28:31], v[134:137]
	v_mfma_f32_16x16x32_bf16 v[200:203], v[208:211], v[56:59], v[200:203]
	v_mfma_f32_16x16x32_bf16 v[204:207], v[208:211], v[36:39], v[204:207]
	v_mfma_f32_16x16x32_bf16 v[114:117], v[208:211], v[44:47], v[114:117]
	ds_read_b64_tr_b16 v[208:209], v220 offset:5120
	ds_read_b64_tr_b16 v[210:211], v220 offset:5440
	s_waitcnt lgkmcnt(0)
	v_mfma_f32_16x16x32_bf16 v[222:225], v[208:211], v[60:63], v[200:203]
	v_mfma_f32_16x16x32_bf16 v[200:203], v[208:211], v[64:67], v[204:207]
	s_nop 2
	ds_read_b64_tr_b16 v[204:205], v220 offset:7680
	ds_read_b64_tr_b16 v[206:207], v220 offset:8000
	s_waitcnt lgkmcnt(0)
	v_mfma_f32_16x16x32_bf16 v[226:229], v[204:207], v[68:71], v[200:203]
	s_waitcnt vmcnt(0)
; #define LAS __attribute__((address_space(3)))
; #define MFMA16(a, b, c) __builtin_amdgcn_mfma_f32_16x16x32_bf16((a), (b), (c), 0, 0, 0)
; __device__ __forceinline__ unsigned pk2(float lo, float hi) { return f2bf(lo) | (f2bf(hi) << 16); }
; __device__ __forceinline__ float bflo(unsigned w) { return __uint_as_float(w << 16); }
; __device__ __forceinline__ float bfhi(unsigned w) { return __uint_as_float(w & 0xffff0000u); }
; __device__ __forceinline__ void sgu_item(LAS unsigned char* wl, const bf16* proj, bf16* ymix, const float* vstat, const float* sgu_g, const bf16* Wm, const float* sgu_b, int chunk, int h, int lane) {
;     ...
;         for (int n = 0; n < 2; ++n) {
;             f32x4 z[8];
; #pragma unroll
;             for (int tb = 0; tb < 8; ++tb) z[tb] = (f32x4){0.f, 0.f, 0.f, 0.f};
;             int f = 0;
; #pragma unroll
;             for (int ks = 0; ks < 4; ++ks) {
;                 LAS unsigned char* ad = wl + (ks * 32 + 8 * q + (r >> 2)) * VP2 + (16 * n) * 2 + 8 * (r & 3);
;                 const s16x4 lo = __builtin_bit_cast(s16x4, __builtin_amdgcn_ds_read_tr16_b64_v4i16((LAS s16x4*)ad));
;                 const s16x4 hi = __builtin_bit_cast(s16x4, __builtin_amdgcn_ds_read_tr16_b64_v4i16((LAS s16x4*)(ad + 4 * VP2)));
;                 const bf16x8 vf = __builtin_shufflevector(lo, hi, 0, 1, 2, 3, 4, 5, 6, 7);
; #pragma unroll
;                 for (int tb = 2 * ks; tb < 8; ++tb) z[tb] = MFMA16(vf, wmf[f++], z[tb]);
;             }
; #pragma unroll
;             for (int tb = 0; tb < 8; ++tb) { const v4u uu = uu8[tb]; const unsigned ux = n == 0 ? uu.x : uu.z, uy = n == 0 ? uu.y : uu.w;
;                 v2u o; o.x = pk2(bflo(ux) * (z[tb][0] + bias[tb]), bfhi(ux) * (z[tb][1] + bias[tb])); o.y = pk2(bflo(uy) * (z[tb][2] + bias[tb]), bfhi(uy) * (z[tb][3] + bias[tb]));
	s_nop 1
	v_and_b32_e32 v201, 0xffff0000, v105
	v_and_b32_e32 v200, 0xffff0000, v104
	v_lshlrev_b32_e32 v105, 16, v105
	v_lshlrev_b32_e32 v104, 16, v104
	v_pk_mul_f32 v[214:215], v[118:119], v[104:105]
	v_mov_b32_e32 v104, v123
	v_mov_b32_e32 v105, v125
	v_pk_add_f32 v[104:105], v[164:165], v[104:105]
	v_and_b32_e32 v119, 0xffff0000, v101
	v_and_b32_e32 v118, 0xffff0000, v100
	v_mov_b32_e32 v123, v124
	v_mfma_f32_16x16x32_bf16 v[114:117], v[208:211], v[72:75], v[114:117]
	v_mul_f32_e64 v212, v104, v118
	v_mul_f32_e64 v213, v105, v119
	v_pk_add_f32 v[104:105], v[164:165], v[122:123]
	v_lshlrev_b32_e32 v101, 16, v101
	v_lshlrev_b32_e32 v100, 16, v100
	v_mfma_f32_16x16x32_bf16 v[134:137], v[208:211], v[52:55], v[134:137]
	v_mul_f32_e64 v210, v104, v100
	v_mul_f32_e64 v211, v105, v101
	v_mov_b32_e32 v100, v127
	v_mov_b32_e32 v101, v129
	v_pk_add_f32 v[100:101], v[166:167], v[100:101]
	v_and_b32_e32 v105, 0xffff0000, v97
	v_and_b32_e32 v104, 0xffff0000, v96
	v_mov_b32_e32 v127, v128
	v_pk_mul_f32 v[208:209], v[100:101], v[104:105]
	v_pk_add_f32 v[100:101], v[166:167], v[126:127]
	v_lshlrev_b32_e32 v97, 16, v97
	v_lshlrev_b32_e32 v96, 16, v96
	v_mfma_f32_16x16x32_bf16 v[114:117], v[204:207], v[76:79], v[114:117]
	v_mul_f32_e64 v206, v100, v96
	v_mul_f32_e64 v207, v101, v97
	v_mov_b32_e32 v96, v131
	v_mov_b32_e32 v97, v133
	v_pk_add_f32 v[96:97], v[168:169], v[96:97]
	v_and_b32_e32 v101, 0xffff0000, v93
	v_and_b32_e32 v100, 0xffff0000, v92
	v_mov_b32_e32 v131, v132
	v_pk_mul_f32 v[204:205], v[96:97], v[100:101]
	v_pk_add_f32 v[96:97], v[168:169], v[130:131]
	v_lshlrev_b32_e32 v93, 16, v93
	v_lshlrev_b32_e32 v92, 16, v92
	v_pk_mul_f32 v[202:203], v[96:97], v[92:93]
	v_mov_b32_e32 v92, v135
	v_mov_b32_e32 v93, v137
	v_pk_add_f32 v[92:93], v[170:171], v[92:93]
	v_and_b32_e32 v97, 0xffff0000, v89
	v_and_b32_e32 v96, 0xffff0000, v88
	v_mov_b32_e32 v135, v136
	v_pk_mul_f32 v[216:217], v[138:139], v[200:201]
	v_pk_mul_f32 v[200:201], v[92:93], v[96:97]
	v_pk_add_f32 v[92:93], v[170:171], v[134:135]
	v_lshlrev_b32_e32 v89, 16, v89
	v_lshlrev_b32_e32 v88, 16, v88
	v_pk_mul_f32 v[104:105], v[92:93], v[88:89]
	v_mov_b32_e32 v88, v223
	v_mov_b32_e32 v89, v225
	v_pk_add_f32 v[88:89], v[172:173], v[88:89]
	v_and_b32_e32 v93, 0xffff0000, v85
	v_and_b32_e32 v92, 0xffff0000, v84
	v_mov_b32_e32 v223, v224
	v_pk_mul_f32 v[100:101], v[88:89], v[92:93]
	v_pk_add_f32 v[88:89], v[172:173], v[222:223]
	v_lshlrev_b32_e32 v85, 16, v85
	v_lshlrev_b32_e32 v84, 16, v84
	v_pk_mul_f32 v[96:97], v[88:89], v[84:85]
	v_mov_b32_e32 v84, v227
	v_mov_b32_e32 v85, v229
	v_pk_add_f32 v[84:85], v[174:175], v[84:85]
	v_and_b32_e32 v89, 0xffff0000, v81
	v_and_b32_e32 v88, 0xffff0000, v80
	v_mov_b32_e32 v227, v228
	v_pk_mul_f32 v[92:93], v[84:85], v[88:89]
	v_pk_add_f32 v[84:85], v[174:175], v[226:227]
	v_lshlrev_b32_e32 v81, 16, v81
	v_lshlrev_b32_e32 v80, 16, v80
	v_pk_mul_f32 v[80:81], v[84:85], v[80:81]
	v_mov_b32_e32 v84, v115
	v_mov_b32_e32 v85, v117
	v_pk_add_f32 v[84:85], v[176:177], v[84:85]
	v_and_b32_e32 v89, 0xffff0000, v109
	v_and_b32_e32 v88, 0xffff0000, v108
	v_mov_b32_e32 v115, v116
	v_pk_mul_f32 v[88:89], v[84:85], v[88:89]
	v_pk_add_f32 v[84:85], v[176:177], v[114:115]
	ds_read_b64_tr_b16 v[114:115], v220 offset:352
	ds_read_b64_tr_b16 v[234:235], v220 offset:2592
	ds_read_b64_tr_b16 v[236:237], v220 offset:2912
	s_waitcnt lgkmcnt(2)
	v_mfma_f32_16x16x32_bf16 v[120:123], v[112:115], v[16:19], 0
	v_lshlrev_b32_e32 v109, 16, v109
	v_lshlrev_b32_e32 v108, 16, v108
	v_pk_mul_f32 v[84:85], v[84:85], v[108:109]
	v_mfma_f32_16x16x32_bf16 v[226:229], v[112:115], v[48:51], 0
	v_bfe_u32 v196, v216, 16, 1
	v_add3_u32 v196, v216, v196, s68
	v_bfe_u32 v195, v217, 16, 1
	v_mfma_f32_16x16x32_bf16 v[230:233], v[112:115], v[32:35], 0
	v_add3_u32 v195, v217, v195, s68
	v_mfma_f32_16x16x32_bf16 v[116:119], v[112:115], v[8:11], 0
	v_mfma_f32_16x16x32_bf16 v[124:127], v[112:115], v[24:27], 0
	v_mfma_f32_16x16x32_bf16 v[222:225], v[112:115], v[0:3], 0
	v_mfma_f32_16x16x32_bf16 v[132:135], v[112:115], v[4:7], 0
	v_mfma_f32_16x16x32_bf16 v[112:115], v[112:115], v[40:43], 0
	s_nop 5
	v_mov_b32_e32 v108, v223
	v_mov_b32_e32 v223, v224
	v_mov_b32_e32 v109, v225
	s_waitcnt lgkmcnt(0)
	v_mfma_f32_16x16x32_bf16 v[128:131], v[234:237], v[20:23], v[120:123]
	v_add_f32_e64 v222, v162, v222
	v_add_f32_e64 v223, v163, v223
	v_pk_add_f32 v[108:109], v[162:163], v[108:109]
	v_mfma_f32_16x16x32_bf16 v[120:123], v[234:237], v[56:59], v[226:229]
	v_mfma_f32_16x16x32_bf16 v[226:229], v[234:237], v[36:39], v[230:233]
	s_nop 2
	ds_read_b64_tr_b16 v[230:231], v220 offset:5152
	ds_read_b64_tr_b16 v[232:233], v220 offset:5472
	v_mfma_f32_16x16x32_bf16 v[136:139], v[234:237], v[12:15], v[116:119]
	v_mfma_f32_16x16x32_bf16 v[116:119], v[234:237], v[28:31], v[124:127]
	v_mfma_f32_16x16x32_bf16 v[112:115], v[234:237], v[44:47], v[112:115]
	s_waitcnt lgkmcnt(0)
	v_mfma_f32_16x16x32_bf16 v[124:127], v[230:233], v[52:55], v[116:119]
	v_mfma_f32_16x16x32_bf16 v[116:119], v[230:233], v[64:67], v[226:229]
	s_nop 2
	ds_read_b64_tr_b16 v[226:227], v220 offset:7712
	ds_read_b64_tr_b16 v[228:229], v220 offset:8032
	v_mfma_f32_16x16x32_bf16 v[112:115], v[230:233], v[72:75], v[112:115]
	s_waitcnt lgkmcnt(0)
; __device__ __forceinline__ unsigned pk2(float lo, float hi) { return f2bf(lo) | (f2bf(hi) << 16); }
; __device__ __forceinline__ float bflo(unsigned w) { return __uint_as_float(w << 16); }
; __device__ __forceinline__ float bfhi(unsigned w) { return __uint_as_float(w & 0xffff0000u); }
; __device__ __forceinline__ void sgu_item(LAS unsigned char* wl, const bf16* proj, bf16* ymix, const float* vstat, const float* sgu_g, const bf16* Wm, const float* sgu_b, int chunk, int h, int lane) {
;     ...
;             for (int tb = 0; tb < 8; ++tb) { const v4u uu = uu8[tb]; const unsigned ux = n == 0 ? uu.x : uu.z, uy = n == 0 ? uu.y : uu.w;
;                 v2u o; o.x = pk2(bflo(ux) * (z[tb][0] + bias[tb]), bfhi(ux) * (z[tb][1] + bias[tb])); o.y = pk2(bflo(uy) * (z[tb][2] + bias[tb]), bfhi(uy) * (z[tb][3] + bias[tb]));
;                 if (n == 0) olo[tb] = o;
;                 else { v4u w; w.x = olo[tb].x; w.y = olo[tb].y; w.z = o.x; w.w = o.y; *(v4u*)(ymix + (R0 + 16 * tb + r) * D + 512 + colv + 8 * q) = w; } }
	v_mfma_f32_16x16x32_bf16 v[116:119], v[226:229], v[68:71], v[116:119]
	v_mfma_f32_16x16x32_bf16 v[112:115], v[226:229], v[76:79], v[112:115]
	v_and_b32_e32 v227, 0xffff0000, v107
	v_and_b32_e32 v226, 0xffff0000, v106
	v_lshlrev_b32_e32 v107, 16, v107
	v_lshlrev_b32_e32 v106, 16, v106
	v_pk_mul_f32 v[106:107], v[222:223], v[106:107]
	v_pk_mul_f32 v[108:109], v[108:109], v[226:227]
	v_bfe_u32 v197, v106, 16, 1
	v_bfe_u32 v216, v107, 16, 1
	v_bfe_u32 v192, v109, 16, 1
	v_bfe_u32 v194, v108, 16, 1
	v_add3_u32 v107, v107, v216, s68
	v_add3_u32 v106, v106, v197, s68
	v_add3_u32 v108, v108, v194, s68
	v_add3_u32 v109, v109, v192, s68
	v_bfe_u32 v192, v214, 16, 1
	v_bfe_u32 v194, v215, 16, 1
	v_lshrrev_b32_e32 v106, 16, v106
	v_lshrrev_b32_e32 v107, 16, v107
	v_add3_u32 v194, v215, v194, s68
	v_add3_u32 v192, v214, v192, s68
	v_and_or_b32 v217, v109, s37, v107
	v_and_or_b32 v216, v108, s37, v106
	v_lshl_add_u64 v[106:107], v[182:183], 0, s[20:21]
	v_lshrrev_b32_e32 v192, 16, v192
	v_lshrrev_b32_e32 v194, 16, v194
	v_add_co_u32_e32 v108, vcc, s0, v106
	v_and_or_b32 v215, v195, s37, v194
	v_and_or_b32 v214, v196, s37, v192
	v_addc_co_u32_e32 v109, vcc, 0, v107, vcc
	global_store_dwordx4 v[108:109], v[214:217], off offset:1024
	v_mov_b32_e32 v108, v133
	v_mov_b32_e32 v109, v135
	v_mov_b32_e32 v133, v134
	v_pk_add_f32 v[108:109], v[164:165], v[108:109]
	v_and_b32_e32 v215, 0xffff0000, v103
	v_and_b32_e32 v214, 0xffff0000, v102
	v_pk_add_f32 v[132:133], v[164:165], v[132:133]
	v_lshlrev_b32_e32 v103, 16, v103
	v_lshlrev_b32_e32 v102, 16, v102
	v_pk_mul_f32 v[108:109], v[108:109], v[214:215]
	v_pk_mul_f32 v[102:103], v[132:133], v[102:103]
	v_bfe_u32 v134, v213, 16, 1
	v_bfe_u32 v132, v109, 16, 1
	v_bfe_u32 v133, v108, 16, 1
	v_bfe_u32 v135, v212, 16, 1
	v_add3_u32 v194, v213, v134, s68
	v_bfe_u32 v134, v102, 16, 1
	v_add3_u32 v192, v212, v135, s68
	v_add3_u32 v108, v108, v133, s68
	v_add3_u32 v109, v109, v132, s68
	v_bfe_u32 v132, v210, 16, 1
	v_bfe_u32 v133, v211, 16, 1
	v_bfe_u32 v135, v103, 16, 1
	v_add3_u32 v102, v102, v134, s68
	v_add3_u32 v103, v103, v135, s68
	v_add3_u32 v133, v211, v133, s68
	v_add3_u32 v132, v210, v132, s68
	v_lshrrev_b32_e32 v102, 16, v102
	s_mov_b32 s0, 0x10908000
	v_lshrrev_b32_e32 v132, 16, v132
	v_lshrrev_b32_e32 v133, 16, v133
	v_lshrrev_b32_e32 v103, 16, v103
	v_and_or_b32 v134, v108, s37, v102
	v_add_co_u32_e32 v102, vcc, s0, v106
	v_and_or_b32 v135, v109, s37, v103
	v_and_or_b32 v133, v194, s37, v133
	v_and_or_b32 v132, v192, s37, v132
	v_addc_co_u32_e32 v103, vcc, 0, v107, vcc
	global_store_dwordx4 v[102:103], v[132:135], off offset:1024
	v_mov_b32_e32 v102, v137
	v_mov_b32_e32 v103, v139
	v_pk_add_f32 v[102:103], v[166:167], v[102:103]
	v_and_b32_e32 v109, 0xffff0000, v99
	v_and_b32_e32 v108, 0xffff0000, v98
	v_mov_b32_e32 v137, v138
	v_pk_mul_f32 v[102:103], v[102:103], v[108:109]
	v_pk_add_f32 v[108:109], v[166:167], v[136:137]
	v_lshlrev_b32_e32 v99, 16, v99
	v_lshlrev_b32_e32 v98, 16, v98
	v_pk_mul_f32 v[98:99], v[108:109], v[98:99]
	v_bfe_u32 v133, v208, 16, 1
	v_bfe_u32 v108, v103, 16, 1
	v_bfe_u32 v109, v102, 16, 1
	v_add3_u32 v136, v208, v133, s68
	v_bfe_u32 v133, v98, 16, 1
	v_add3_u32 v102, v102, v109, s68
	v_add3_u32 v103, v103, v108, s68
	v_bfe_u32 v108, v206, 16, 1
	v_bfe_u32 v109, v207, 16, 1
	v_bfe_u32 v134, v99, 16, 1
	v_add3_u32 v98, v98, v133, s68
	v_bfe_u32 v132, v209, 16, 1
	v_add3_u32 v99, v99, v134, s68
	v_add3_u32 v109, v207, v109, s68
	v_add3_u32 v108, v206, v108, s68
	v_lshrrev_b32_e32 v98, 16, v98
	s_mov_b32 s0, 0x10910000
	v_add3_u32 v132, v209, v132, s68
	v_lshrrev_b32_e32 v108, 16, v108
	v_lshrrev_b32_e32 v109, 16, v109
	v_lshrrev_b32_e32 v99, 16, v99
	v_and_or_b32 v134, v102, s37, v98
	v_add_co_u32_e32 v98, vcc, s0, v106
	v_and_or_b32 v135, v103, s37, v99
	v_and_or_b32 v133, v132, s37, v109
	v_and_or_b32 v132, v136, s37, v108
	v_addc_co_u32_e32 v99, vcc, 0, v107, vcc
	global_store_dwordx4 v[98:99], v[132:135], off offset:1024
	v_mov_b32_e32 v98, v129
	v_mov_b32_e32 v99, v131
	v_pk_add_f32 v[98:99], v[168:169], v[98:99]
	v_and_b32_e32 v103, 0xffff0000, v95
	v_and_b32_e32 v102, 0xffff0000, v94
	v_mov_b32_e32 v129, v130
	v_pk_mul_f32 v[98:99], v[98:99], v[102:103]
	v_pk_add_f32 v[102:103], v[168:169], v[128:129]
	v_lshlrev_b32_e32 v95, 16, v95
	v_lshlrev_b32_e32 v94, 16, v94
	v_pk_mul_f32 v[94:95], v[102:103], v[94:95]
	v_bfe_u32 v102, v99, 16, 1
	v_bfe_u32 v103, v98, 16, 1
	v_add3_u32 v98, v98, v103, s68
	v_add3_u32 v99, v99, v102, s68
	v_bfe_u32 v102, v202, 16, 1
	v_bfe_u32 v103, v203, 16, 1
	v_bfe_u32 v128, v94, 16, 1
	v_bfe_u32 v129, v95, 16, 1
	v_bfe_u32 v108, v205, 16, 1
	v_bfe_u32 v109, v204, 16, 1
	v_add3_u32 v95, v95, v129, s68
	v_add3_u32 v94, v94, v128, s68
	v_add3_u32 v103, v203, v103, s68
	v_add3_u32 v102, v202, v102, s68
	v_add3_u32 v109, v204, v109, s68
	v_add3_u32 v108, v205, v108, s68
	v_lshrrev_b32_e32 v102, 16, v102
	v_lshrrev_b32_e32 v103, 16, v103
	v_lshrrev_b32_e32 v94, 16, v94
	v_lshrrev_b32_e32 v95, 16, v95
	v_and_or_b32 v131, v99, s37, v95
	v_and_or_b32 v130, v98, s37, v94
	v_and_or_b32 v129, v108, s37, v103
	v_and_or_b32 v128, v109, s37, v102
	v_lshl_add_u64 v[94:95], v[184:185], 0, s[20:21]
	global_store_dwordx4 v[94:95], v[128:131], off
	v_mov_b32_e32 v94, v125
	v_mov_b32_e32 v95, v127
	v_pk_add_f32 v[94:95], v[170:171], v[94:95]
; __device__ __forceinline__ unsigned pk2(float lo, float hi) { return f2bf(lo) | (f2bf(hi) << 16); }
; __device__ __forceinline__ float bflo(unsigned w) { return __uint_as_float(w << 16); }
; __device__ __forceinline__ float bfhi(unsigned w) { return __uint_as_float(w & 0xffff0000u); }
; #define LDS_WAIT() asm volatile("s_waitcnt lgkmcnt(0)" ::: "memory")
; #define lane (hw_lane())
; __device__ __forceinline__ void sgu_item(LAS unsigned char* wl, const bf16* proj, bf16* ymix, const float* vstat, const float* sgu_g, const bf16* Wm, const float* sgu_b, int chunk, int h, int lane) {
;     ...
;             for (int tb = 0; tb < 8; ++tb) { const v4u uu = uu8[tb]; const unsigned ux = n == 0 ? uu.x : uu.z, uy = n == 0 ? uu.y : uu.w;
;                 v2u o; o.x = pk2(bflo(ux) * (z[tb][0] + bias[tb]), bfhi(ux) * (z[tb][1] + bias[tb])); o.y = pk2(bflo(uy) * (z[tb][2] + bias[tb]), bfhi(uy) * (z[tb][3] + bias[tb]));
;                 if (n == 0) olo[tb] = o;
;                 else { v4u w; w.x = olo[tb].x; w.y = olo[tb].y; w.z = o.x; w.w = o.y; *(v4u*)(ymix + (R0 + 16 * tb + r) * D + 512 + colv + 8 * q) = w; } }
;         }
;         LDS_WAIT();
;     }
; __device__ __forceinline__ void mixer_phase(LAS unsigned char* lds, const bf16* proj, bf16* ymix, const float* vstat, const bf16* WpT, const float* pscale, const float* sgu_g, const bf16* Wm, const float* sgu_b, int pool_first, int pool_step, int pool_limit, int sgu_first, int sgu_step, int sgu_limi ...
;     ...
;     for (int j = sgu_first; j < sgu_limit; j += sgu_step) sgu_item(wl, proj, ymix, vstat, sgu_g, Wm, sgu_b, j >> 2, j & 3, lane);
	v_and_b32_e32 v99, 0xffff0000, v91
	v_and_b32_e32 v98, 0xffff0000, v90
	v_mov_b32_e32 v125, v126
	v_pk_mul_f32 v[94:95], v[94:95], v[98:99]
	v_pk_add_f32 v[98:99], v[170:171], v[124:125]
	v_lshlrev_b32_e32 v91, 16, v91
	v_lshlrev_b32_e32 v90, 16, v90
	v_pk_mul_f32 v[90:91], v[98:99], v[90:91]
	v_bfe_u32 v103, v200, 16, 1
	v_bfe_u32 v98, v95, 16, 1
	v_bfe_u32 v99, v94, 16, 1
	v_add3_u32 v108, v200, v103, s68
	v_bfe_u32 v103, v90, 16, 1
	v_mfma_f32_16x16x32_bf16 v[120:123], v[230:233], v[60:63], v[120:123]
	v_add3_u32 v94, v94, v99, s68
	v_add3_u32 v95, v95, v98, s68
	v_bfe_u32 v98, v104, 16, 1
	v_bfe_u32 v99, v105, 16, 1
	v_bfe_u32 v109, v91, 16, 1
	v_add3_u32 v90, v90, v103, s68
	v_bfe_u32 v102, v201, 16, 1
	v_add3_u32 v91, v91, v109, s68
	v_add3_u32 v99, v105, v99, s68
	v_add3_u32 v98, v104, v98, s68
	v_lshrrev_b32_e32 v90, 16, v90
	s_mov_b32 s0, 0x10920000
	v_add3_u32 v102, v201, v102, s68
	v_lshrrev_b32_e32 v98, 16, v98
	v_lshrrev_b32_e32 v99, 16, v99
	v_lshrrev_b32_e32 v91, 16, v91
	v_and_or_b32 v104, v94, s37, v90
	v_add_co_u32_e32 v90, vcc, s0, v106
	v_and_or_b32 v105, v95, s37, v91
	v_and_or_b32 v103, v102, s37, v99
	v_and_or_b32 v102, v108, s37, v98
	v_addc_co_u32_e32 v91, vcc, 0, v107, vcc
	global_store_dwordx4 v[90:91], v[102:105], off offset:1024
	v_mov_b32_e32 v90, v121
	v_mov_b32_e32 v91, v123
	v_pk_add_f32 v[90:91], v[172:173], v[90:91]
	v_and_b32_e32 v95, 0xffff0000, v87
	v_and_b32_e32 v94, 0xffff0000, v86
	v_mov_b32_e32 v121, v122
	v_pk_mul_f32 v[90:91], v[90:91], v[94:95]
	v_pk_add_f32 v[94:95], v[172:173], v[120:121]
	v_lshlrev_b32_e32 v87, 16, v87
	v_lshlrev_b32_e32 v86, 16, v86
	v_pk_mul_f32 v[86:87], v[94:95], v[86:87]
	v_bfe_u32 v99, v100, 16, 1
	v_bfe_u32 v94, v91, 16, 1
	v_bfe_u32 v95, v90, 16, 1
	v_bfe_u32 v98, v101, 16, 1
	v_add3_u32 v99, v100, v99, s68
	v_bfe_u32 v100, v86, 16, 1
	v_add3_u32 v98, v101, v98, s68
	v_add3_u32 v90, v90, v95, s68
	v_add3_u32 v91, v91, v94, s68
	v_bfe_u32 v94, v96, 16, 1
	v_bfe_u32 v95, v97, 16, 1
	v_bfe_u32 v101, v87, 16, 1
	v_add3_u32 v86, v86, v100, s68
	v_add3_u32 v87, v87, v101, s68
	v_add3_u32 v95, v97, v95, s68
	v_add3_u32 v94, v96, v94, s68
	v_lshrrev_b32_e32 v86, 16, v86
	s_mov_b32 s0, 0x10928000
	v_lshrrev_b32_e32 v94, 16, v94
	v_lshrrev_b32_e32 v95, 16, v95
	v_lshrrev_b32_e32 v87, 16, v87
	v_and_or_b32 v96, v90, s37, v86
	v_add_co_u32_e32 v86, vcc, s0, v106
	v_and_or_b32 v97, v91, s37, v87
	v_and_or_b32 v95, v98, s37, v95
	v_and_or_b32 v94, v99, s37, v94
	v_addc_co_u32_e32 v87, vcc, 0, v107, vcc
	global_store_dwordx4 v[86:87], v[94:97], off offset:1024
	v_mov_b32_e32 v86, v117
	v_mov_b32_e32 v87, v119
	v_pk_add_f32 v[86:87], v[174:175], v[86:87]
	v_and_b32_e32 v91, 0xffff0000, v83
	v_and_b32_e32 v90, 0xffff0000, v82
	v_mov_b32_e32 v117, v118
	v_pk_mul_f32 v[86:87], v[86:87], v[90:91]
	v_pk_add_f32 v[90:91], v[174:175], v[116:117]
	v_lshlrev_b32_e32 v83, 16, v83
	v_lshlrev_b32_e32 v82, 16, v82
	v_pk_mul_f32 v[82:83], v[90:91], v[82:83]
	v_bfe_u32 v94, v93, 16, 1
	v_bfe_u32 v90, v87, 16, 1
	v_bfe_u32 v91, v86, 16, 1
	v_bfe_u32 v95, v92, 16, 1
	v_add3_u32 v93, v93, v94, s68
	v_bfe_u32 v94, v82, 16, 1
	v_add3_u32 v92, v92, v95, s68
	v_add3_u32 v86, v86, v91, s68
	v_add3_u32 v87, v87, v90, s68
	v_bfe_u32 v90, v80, 16, 1
	v_bfe_u32 v91, v81, 16, 1
	v_bfe_u32 v95, v83, 16, 1
	v_add3_u32 v82, v82, v94, s68
	v_add3_u32 v83, v83, v95, s68
	v_add3_u32 v81, v81, v91, s68
	v_add3_u32 v80, v80, v90, s68
	v_lshrrev_b32_e32 v82, 16, v82
	s_mov_b32 s0, 0x10930000
	v_lshrrev_b32_e32 v80, 16, v80
	v_lshrrev_b32_e32 v81, 16, v81
	v_lshrrev_b32_e32 v83, 16, v83
	v_and_or_b32 v82, v86, s37, v82
	v_add_co_u32_e32 v86, vcc, s0, v106
	v_and_or_b32 v83, v87, s37, v83
	v_and_or_b32 v81, v93, s37, v81
	v_and_or_b32 v80, v92, s37, v80
	v_addc_co_u32_e32 v87, vcc, 0, v107, vcc
	global_store_dwordx4 v[86:87], v[80:83], off offset:1024
	v_lshlrev_b32_e32 v87, 16, v111
	v_lshlrev_b32_e32 v86, 16, v110
	v_mov_b32_e32 v80, v113
	v_mov_b32_e32 v81, v115
	v_pk_add_f32 v[80:81], v[176:177], v[80:81]
	v_and_b32_e32 v83, 0xffff0000, v111
	v_and_b32_e32 v82, 0xffff0000, v110
	v_mov_b32_e32 v113, v114
	v_pk_mul_f32 v[80:81], v[80:81], v[82:83]
	v_pk_add_f32 v[82:83], v[176:177], v[112:113]
	v_bfe_u32 v90, v89, 16, 1
	v_pk_mul_f32 v[82:83], v[82:83], v[86:87]
	v_bfe_u32 v86, v81, 16, 1
	v_bfe_u32 v87, v80, 16, 1
	v_bfe_u32 v91, v88, 16, 1
	v_add3_u32 v88, v88, v91, s68
	v_add3_u32 v89, v89, v90, s68
	v_add3_u32 v80, v80, v87, s68
	v_add3_u32 v81, v81, v86, s68
	v_bfe_u32 v86, v84, 16, 1
	v_bfe_u32 v87, v85, 16, 1
	v_bfe_u32 v90, v82, 16, 1
	v_bfe_u32 v91, v83, 16, 1
	v_add3_u32 v83, v83, v91, s68
	v_add3_u32 v82, v82, v90, s68
	v_add3_u32 v85, v85, v87, s68
	v_add3_u32 v84, v84, v86, s68
	v_lshrrev_b32_e32 v84, 16, v84
	v_lshrrev_b32_e32 v85, 16, v85
	v_lshrrev_b32_e32 v82, 16, v82
	v_lshrrev_b32_e32 v83, 16, v83
	v_and_or_b32 v83, v81, s37, v83
	v_and_or_b32 v82, v80, s37, v82
	v_and_or_b32 v81, v89, s37, v85
	v_and_or_b32 v80, v88, s37, v84
	v_lshl_add_u64 v[84:85], v[180:181], 0, s[20:21]
	global_store_dwordx4 v[84:85], v[80:83], off
	s_waitcnt lgkmcnt(0)
	s_add_u32 s20, s20, 64
	s_addc_u32 s21, s21, 0
	s_cmpk_lg_i32 s20, 0x100
	s_cbranch_scc1 .LBB0_511
	s_add_i32 s5, s5, s77
	s_add_i32 s4, s4, s7
	s_cmp_lt_i32 s5, s2
	s_cbranch_scc1 .LBB0_510
